# lever 7 (instruction count): GEMM phases drop the per-tile 127 v_mov accumulator zeroing; first k-iteration peeled with inline-0 C operand on each accumulator's first MFMA (bit-identical)
# speedup vs baseline: 1.0022x; 1.0022x over previous
; #define PG8_STAGE(bufoff, gbase, voff) do { _Pragma("unroll") for (int _i = 0; _i < 2; ++_i) \
;         __builtin_amdgcn_global_load_lds((const unsigned*)((const char*)(gbase) + (voff)[_i]), (LAS unsigned*)(lds + (bufoff) + ldsw + _i * 8192), 16, 0, 0); } while (0)
; #define PG8_LDA(dst, b, h) do { _Pragma("unroll") for (int m = 0; m < 4; ++m) _Pragma("unroll") for (int k = 0; k < 2; ++k) dst[m][k] = *(const LAS bf16x8*)(lds + PG8_SA(b, h) + aoff + m * 2048 + k * 1024); } while (0)
; #define PG8_LDB(dst, b, h) do { _Pragma("unroll") for (int n = 0; n < 2; ++n) _Pragma("unroll") for (int k = 0; k < 2; ++k) dst[n][k] = *(const LAS bf16x8*)(lds + PG8_SB(b, h) + boff + n * 2048 + k * 1024); } while (0)
; #define PG8_BAR __builtin_amdgcn_s_barrier()
; template <class Epi, class Sched, bool ALIGN_EPI = true>
; __device__ __forceinline__ void gemm_phase(LAS unsigned char* lds, const int wave_s, const int K, const Sched& S, const Epi& E) {
;     ...
;     PG8_STAGE(PG8_SB(0, 0), cB, voffB); PG8_STAGE(PG8_SB(0, 1), cB + hstep, voffB); PG8_STAGE(PG8_SA(0, 0), cA, voffA); PG8_STAGE(PG8_SA(0, 1), cA + hstep, voffA);
;     if (wr == 1) PG8_BAR;
;     PG8_WAIT_V(2); PG8_BAR;
;     PG8_STAGE(PG8_SB(1, 0), cB + kstep, voffB); PG8_STAGE(PG8_SA(1, 0), cA + kstep, voffA); PG8_STAGE(PG8_SB(1, 1), cB + hstep + kstep, voffB);
;     PG8_WAIT_V(6); PG8_BAR;
;     for (;;) {
;         const bool has_next = S.next(ui + 1, nxt);
;         const char* nA = has_next ? S.aptr(nxt) : cA; const char* nB = has_next ? S.bptr(nxt) : cB;
;         for (int t = 0; t < nt; t += 2) {
;             const bool last = (t == nt - 2);
;             const char* a1 = cA + (size_t)(t + 1) * kstep;
;             const char* a2 = last ? nA : cA + (size_t)(t + 2) * kstep; const char* b2 = last ? nB : cB + (size_t)(t + 2) * kstep;
;             const char* a3 = a2 + kstep; const char* b3 = b2 + kstep;
;             PG8_LDB(B0, 0, 0); PG8_LDB(B1, 0, 1); PG8_SCHED; PG8_LDA(At, 0, 0); PG8_STAGE(PG8_SA(1, 1), a1 + hstep, voffA);
;             PG8_WAIT_V(8); PG8_WAIT_L(0); PG8_BAR; PG8_MMA(0, 0, At, B0); PG8_MMA(0, 1, At, B1); PG8_BAR; PG8_SCHED;
;             PG8_LDA(At, 0, 1); PG8_STAGE(PG8_SB(0, 0), b2, voffB); PG8_STAGE(PG8_SB(0, 1), b2 + hstep, voffB); PG8_STAGE(PG8_SA(0, 0), a2, voffA);
;             PG8_WAIT_V(8); PG8_WAIT_L(0); PG8_BAR; PG8_MMA(1, 0, At, B0); PG8_MMA(1, 1, At, B1); PG8_BAR; PG8_SCHED;
.LBB0_64:
	s_ashr_i32 s71, s70, 31
	s_lshl_b64 s[54:55], s[70:71], 21
	s_add_u32 s76, s7, s54
	s_addc_u32 s77, s16, s55
	s_and_b64 s[54:55], s[48:49], exec
	s_cselect_b32 s68, s77, s13
	s_cselect_b32 s69, s76, s12
	s_ashr_i32 s65, s64, 31
	s_lshl_b64 s[54:55], s[64:65], 21
	s_add_u32 s90, s18, s54
	s_addc_u32 s91, s19, s55
	s_and_b64 s[54:55], s[48:49], exec
	s_cselect_b32 s65, s91, s51
	s_cselect_b32 s71, s90, s50
	s_add_u32 s12, s12, 0x100080
	s_addc_u32 s13, s13, 0
	s_add_u32 s79, s50, 0x100
	s_addc_u32 s80, s51, 0
	s_mov_b32 s81, -2
	s_add_u32 s50, s12, 0xfff00080
	s_addc_u32 s51, s13, -1
	s_add_i32 s83, 0, 0x10000
	s_cmp_eq_u32 s81, 60
	s_cselect_b32 s55, s68, s51
	s_cselect_b32 s54, s69, s50
	s_cselect_b32 s51, s65, s80
	s_cselect_b32 s50, s71, s79
	s_add_i32 s95, 0, 0x14000
	v_add_u32_e32 v154, s83, v171
	v_add_u32_e32 v158, s95, v171
	ds_read_b128 v[142:145], v154
	ds_read_b128 v[146:149], v154 offset:1024
	ds_read_b128 v[150:153], v154 offset:2048
	ds_read_b128 v[154:157], v154 offset:3072
	ds_read_b128 v[166:169], v158
	ds_read_b128 v[202:205], v158 offset:1024
	ds_read_b128 v[206:209], v158 offset:2048
	ds_read_b128 v[210:213], v158 offset:3072
	v_lshl_add_u64 v[158:159], s[12:13], 0, v[138:139]
	s_add_i32 m0, s20, 0xc000
	ds_read_b128 v[214:217], v191
	ds_read_b128 v[218:221], v191 offset:1024
	ds_read_b128 v[222:225], v191 offset:2048
	ds_read_b128 v[226:229], v191 offset:3072
	ds_read_b128 v[230:233], v191 offset:4096
	ds_read_b128 v[234:237], v191 offset:5120
	ds_read_b128 v[238:241], v191 offset:6144
	ds_read_b128 v[242:245], v191 offset:7168
	global_load_lds_dwordx4 v[158:159], off
	v_lshl_add_u64 v[158:159], s[12:13], 0, v[140:141]
	s_add_i32 m0, s20, 0xe000
	s_nop 0
	global_load_lds_dwordx4 v[158:159], off
	s_waitcnt vmcnt(8)
	s_waitcnt lgkmcnt(0)
	s_barrier
	s_setprio 1
	s_waitcnt lgkmcnt(0)
	v_mfma_f32_16x16x32_bf16 v[50:53], v[142:145], v[214:217], 0
	v_mfma_f32_16x16x32_bf16 v[54:57], v[150:153], v[214:217], 0
	v_mfma_f32_16x16x32_bf16 v[74:77], v[142:145], v[222:225], 0
	v_mfma_f32_16x16x32_bf16 v[78:81], v[150:153], v[222:225], 0
	v_mfma_f32_16x16x32_bf16 v[98:101], v[142:145], v[230:233], 0
	v_mfma_f32_16x16x32_bf16 v[102:105], v[150:153], v[230:233], 0
	v_mfma_f32_16x16x32_bf16 v[126:129], v[142:145], v[238:241], 0
	v_mfma_f32_16x16x32_bf16 v[122:125], v[150:153], v[238:241], 0
	v_mfma_f32_16x16x32_bf16 v[50:53], v[146:149], v[218:221], v[50:53]
	v_mfma_f32_16x16x32_bf16 v[54:57], v[154:157], v[218:221], v[54:57]
	v_mfma_f32_16x16x32_bf16 v[74:77], v[146:149], v[226:229], v[74:77]
	v_mfma_f32_16x16x32_bf16 v[78:81], v[154:157], v[226:229], v[78:81]
	v_mfma_f32_16x16x32_bf16 v[98:101], v[146:149], v[234:237], v[98:101]
	v_mfma_f32_16x16x32_bf16 v[102:105], v[154:157], v[234:237], v[102:105]
	v_mfma_f32_16x16x32_bf16 v[126:129], v[146:149], v[242:245], v[126:129]
	v_mfma_f32_16x16x32_bf16 v[122:125], v[154:157], v[242:245], v[122:125]
	s_setprio 0
	s_setprio 1
	v_mfma_f32_16x16x32_bf16 v[62:65], v[166:169], v[214:217], 0
	v_mfma_f32_16x16x32_bf16 v[58:61], v[206:209], v[214:217], 0
	v_mfma_f32_16x16x32_bf16 v[94:97], v[166:169], v[222:225], 0
	v_mfma_f32_16x16x32_bf16 v[90:93], v[206:209], v[222:225], 0
	v_mfma_f32_16x16x32_bf16 v[118:121], v[166:169], v[230:233], 0
	v_mfma_f32_16x16x32_bf16 v[114:117], v[206:209], v[230:233], 0
	v_mfma_f32_16x16x32_bf16 v[110:113], v[166:169], v[238:241], 0
	v_mfma_f32_16x16x32_bf16 v[106:109], v[206:209], v[238:241], 0
	v_mfma_f32_16x16x32_bf16 v[62:65], v[202:205], v[218:221], v[62:65]
	v_mfma_f32_16x16x32_bf16 v[58:61], v[210:213], v[218:221], v[58:61]
	v_mfma_f32_16x16x32_bf16 v[94:97], v[202:205], v[226:229], v[94:97]
	v_mfma_f32_16x16x32_bf16 v[90:93], v[210:213], v[226:229], v[90:93]
	v_mfma_f32_16x16x32_bf16 v[118:121], v[202:205], v[234:237], v[118:121]
	v_mfma_f32_16x16x32_bf16 v[114:117], v[210:213], v[234:237], v[114:117]
	v_mfma_f32_16x16x32_bf16 v[110:113], v[202:205], v[242:245], v[110:113]
	v_mfma_f32_16x16x32_bf16 v[106:109], v[210:213], v[242:245], v[106:109]
	s_setprio 0
	s_barrier
	s_add_i32 s83, s83, s33
	v_lshl_add_u64 v[158:159], s[50:51], 0, v[0:1]
	s_mov_b32 m0, s83
	ds_read_b128 v[214:217], v191 offset:16384
	ds_read_b128 v[218:221], v191 offset:17408
	ds_read_b128 v[222:225], v191 offset:18432
	ds_read_b128 v[226:229], v191 offset:19456
	ds_read_b128 v[230:233], v191 offset:20480
	ds_read_b128 v[234:237], v191 offset:21504
	ds_read_b128 v[238:241], v191 offset:22528
	ds_read_b128 v[242:245], v191 offset:23552
	global_load_lds_dwordx4 v[158:159], off
	s_add_i32 m0, s83, 0x2000
	s_add_u32 s84, s50, 0x100000
	v_lshl_add_u64 v[160:161], s[50:51], 0, v[134:135]
	s_addc_u32 s85, s51, 0
	s_add_i32 s83, s95, s33
	global_load_lds_dwordx4 v[160:161], off
	v_lshl_add_u64 v[162:163], s[84:85], 0, v[0:1]
	s_mov_b32 m0, s83
	v_lshl_add_u64 v[164:165], s[54:55], 0, v[132:133]
	global_load_lds_dwordx4 v[162:163], off
	v_lshl_add_u64 v[162:163], s[84:85], 0, v[134:135]
	s_add_i32 m0, s83, 0x2000
	s_nop 0
	global_load_lds_dwordx4 v[162:163], off
	v_lshl_add_u64 v[162:163], s[54:55], 0, v[130:131]
	s_mov_b32 m0, s20
	s_nop 0
	global_load_lds_dwordx4 v[162:163], off
	s_mov_b32 m0, s21
	s_nop 0
	global_load_lds_dwordx4 v[164:165], off
	s_waitcnt vmcnt(8)
	s_waitcnt lgkmcnt(0)
	s_barrier
; #define PG8_STAGE(bufoff, gbase, voff) do { _Pragma("unroll") for (int _i = 0; _i < 2; ++_i) \
;         __builtin_amdgcn_global_load_lds((const unsigned*)((const char*)(gbase) + (voff)[_i]), (LAS unsigned*)(lds + (bufoff) + ldsw + _i * 8192), 16, 0, 0); } while (0)
; #define PG8_LDA(dst, b, h) do { _Pragma("unroll") for (int m = 0; m < 4; ++m) _Pragma("unroll") for (int k = 0; k < 2; ++k) dst[m][k] = *(const LAS bf16x8*)(lds + PG8_SA(b, h) + aoff + m * 2048 + k * 1024); } while (0)
; #define PG8_LDB(dst, b, h) do { _Pragma("unroll") for (int n = 0; n < 2; ++n) _Pragma("unroll") for (int k = 0; k < 2; ++k) dst[n][k] = *(const LAS bf16x8*)(lds + PG8_SB(b, h) + boff + n * 2048 + k * 1024); } while (0)
; #define PG8_MMA(ai, bj, At, Bt) do { __builtin_amdgcn_s_setprio(1); _Pragma("unroll") for (int m = 0; m < 4; ++m) _Pragma("unroll") for (int n = 0; n < 2; ++n) _Pragma("unroll") for (int k = 0; k < 2; ++k) \
;         acc[ai][bj][m][n] = __builtin_amdgcn_mfma_f32_16x16x32_bf16(Bt[n][k], At[m][k], acc[ai][bj][m][n], 0, 0, 0); __builtin_amdgcn_s_setprio(0); } while (0)
; #define PG8_WAIT_V(n) asm volatile("s_waitcnt vmcnt(" #n ")" ::: "memory")
; #define PG8_WAIT_L(n) asm volatile("s_waitcnt lgkmcnt(" #n ")" ::: "memory")
; #define PG8_BAR __builtin_amdgcn_s_barrier()
; #define PG8_SCHED __builtin_amdgcn_sched_barrier(0)
; template <class Epi, class Sched, bool ALIGN_EPI = true>
; __device__ __forceinline__ void gemm_phase(LAS unsigned char* lds, const int wave_s, const int K, const Sched& S, const Epi& E) {
;     ...
;             PG8_WAIT_V(8); PG8_WAIT_L(0); PG8_BAR; PG8_MMA(1, 0, At, B0); PG8_MMA(1, 1, At, B1); PG8_BAR; PG8_SCHED;
;             PG8_LDB(B0, 1, 0); PG8_LDB(B1, 1, 1); PG8_SCHED; PG8_LDA(At, 1, 0); PG8_STAGE(PG8_SA(0, 1), a2 + hstep, voffA);
;             PG8_WAIT_V(8); PG8_WAIT_L(0); PG8_BAR; PG8_MMA(0, 0, At, B0); PG8_MMA(0, 1, At, B1); PG8_BAR; PG8_SCHED;
;             PG8_LDA(At, 1, 1); PG8_STAGE(PG8_SB(1, 0), b3, voffB); PG8_STAGE(PG8_SB(1, 1), b3 + hstep, voffB); PG8_STAGE(PG8_SA(1, 0), a3, voffA);
	s_setprio 1
	s_waitcnt lgkmcnt(0)
	v_mfma_f32_16x16x32_bf16 v[86:89], v[142:145], v[214:217], 0
	v_mfma_f32_16x16x32_bf16 v[82:85], v[150:153], v[214:217], 0
	v_mfma_f32_16x16x32_bf16 v[46:49], v[142:145], v[222:225], 0
	v_mfma_f32_16x16x32_bf16 v[42:45], v[150:153], v[222:225], 0
	v_mfma_f32_16x16x32_bf16 v[30:33], v[142:145], v[230:233], 0
	v_mfma_f32_16x16x32_bf16 v[26:29], v[150:153], v[230:233], 0
	v_mfma_f32_16x16x32_bf16 v[14:17], v[142:145], v[238:241], 0
	v_mfma_f32_16x16x32_bf16 v[10:13], v[150:153], v[238:241], 0
	v_mfma_f32_16x16x32_bf16 v[86:89], v[146:149], v[218:221], v[86:89]
	v_mfma_f32_16x16x32_bf16 v[82:85], v[154:157], v[218:221], v[82:85]
	v_mfma_f32_16x16x32_bf16 v[46:49], v[146:149], v[226:229], v[46:49]
	v_mfma_f32_16x16x32_bf16 v[42:45], v[154:157], v[226:229], v[42:45]
	v_mfma_f32_16x16x32_bf16 v[30:33], v[146:149], v[234:237], v[30:33]
	v_mfma_f32_16x16x32_bf16 v[26:29], v[154:157], v[234:237], v[26:29]
	v_mfma_f32_16x16x32_bf16 v[14:17], v[146:149], v[242:245], v[14:17]
	v_mfma_f32_16x16x32_bf16 v[10:13], v[154:157], v[242:245], v[10:13]
	s_setprio 0
	s_setprio 1
	v_mfma_f32_16x16x32_bf16 v[70:73], v[166:169], v[214:217], 0
	v_mfma_f32_16x16x32_bf16 v[66:69], v[206:209], v[214:217], 0
	v_mfma_f32_16x16x32_bf16 v[38:41], v[166:169], v[222:225], 0
	v_mfma_f32_16x16x32_bf16 v[34:37], v[206:209], v[222:225], 0
	v_mfma_f32_16x16x32_bf16 v[22:25], v[166:169], v[230:233], 0
	v_mfma_f32_16x16x32_bf16 v[18:21], v[206:209], v[230:233], 0
	v_mfma_f32_16x16x32_bf16 v[6:9], v[166:169], v[238:241], 0
	v_mfma_f32_16x16x32_bf16 v[2:5], v[206:209], v[238:241], 0
	v_mfma_f32_16x16x32_bf16 v[70:73], v[202:205], v[218:221], v[70:73]
	v_mfma_f32_16x16x32_bf16 v[66:69], v[210:213], v[218:221], v[66:69]
	v_mfma_f32_16x16x32_bf16 v[38:41], v[202:205], v[226:229], v[38:41]
	v_mfma_f32_16x16x32_bf16 v[34:37], v[210:213], v[226:229], v[34:37]
	v_mfma_f32_16x16x32_bf16 v[22:25], v[202:205], v[234:237], v[22:25]
	v_mfma_f32_16x16x32_bf16 v[18:21], v[210:213], v[234:237], v[18:21]
	v_mfma_f32_16x16x32_bf16 v[6:9], v[202:205], v[242:245], v[6:9]
	v_mfma_f32_16x16x32_bf16 v[2:5], v[210:213], v[242:245], v[2:5]
	s_setprio 0
	s_barrier
	s_add_i32 s83, 0, 0x18000
	s_add_i32 s84, 0, 0x1c000
	v_add_u32_e32 v154, s83, v171
	v_add_u32_e32 v192, s84, v171
	ds_read_b128 v[142:145], v154
	ds_read_b128 v[146:149], v154 offset:1024
	ds_read_b128 v[150:153], v154 offset:2048
	ds_read_b128 v[154:157], v154 offset:3072
	ds_read_b128 v[166:169], v192
	ds_read_b128 v[202:205], v192 offset:1024
	ds_read_b128 v[206:209], v192 offset:2048
	ds_read_b128 v[210:213], v192 offset:3072
	s_add_u32 s54, s54, 0x100000
	s_addc_u32 s55, s55, 0
	s_mov_b32 m0, s28
	v_lshl_add_u64 v[196:197], s[54:55], 0, v[130:131]
	ds_read_b128 v[214:217], v191 offset:32768
	ds_read_b128 v[218:221], v191 offset:33792
	ds_read_b128 v[222:225], v191 offset:34816
	ds_read_b128 v[226:229], v191 offset:35840
	ds_read_b128 v[230:233], v191 offset:36864
	ds_read_b128 v[234:237], v191 offset:37888
	ds_read_b128 v[238:241], v191 offset:38912
	ds_read_b128 v[242:245], v191 offset:39936
	global_load_lds_dwordx4 v[196:197], off
	v_lshl_add_u64 v[196:197], s[54:55], 0, v[132:133]
	s_mov_b32 m0, s30
	s_nop 0
	global_load_lds_dwordx4 v[196:197], off
	s_waitcnt vmcnt(8)
	s_waitcnt lgkmcnt(0)
	s_barrier
	s_setprio 1
	s_waitcnt lgkmcnt(0)
	v_mfma_f32_16x16x32_bf16 v[50:53], v[142:145], v[214:217], v[50:53]
	v_mfma_f32_16x16x32_bf16 v[54:57], v[150:153], v[214:217], v[54:57]
	v_mfma_f32_16x16x32_bf16 v[74:77], v[142:145], v[222:225], v[74:77]
	v_mfma_f32_16x16x32_bf16 v[78:81], v[150:153], v[222:225], v[78:81]
	v_mfma_f32_16x16x32_bf16 v[98:101], v[142:145], v[230:233], v[98:101]
	v_mfma_f32_16x16x32_bf16 v[102:105], v[150:153], v[230:233], v[102:105]
	v_mfma_f32_16x16x32_bf16 v[126:129], v[142:145], v[238:241], v[126:129]
	v_mfma_f32_16x16x32_bf16 v[122:125], v[150:153], v[238:241], v[122:125]
	v_mfma_f32_16x16x32_bf16 v[50:53], v[146:149], v[218:221], v[50:53]
	v_mfma_f32_16x16x32_bf16 v[54:57], v[154:157], v[218:221], v[54:57]
	v_mfma_f32_16x16x32_bf16 v[74:77], v[146:149], v[226:229], v[74:77]
	v_mfma_f32_16x16x32_bf16 v[78:81], v[154:157], v[226:229], v[78:81]
	v_mfma_f32_16x16x32_bf16 v[98:101], v[146:149], v[234:237], v[98:101]
	v_mfma_f32_16x16x32_bf16 v[102:105], v[154:157], v[234:237], v[102:105]
	v_mfma_f32_16x16x32_bf16 v[126:129], v[146:149], v[242:245], v[126:129]
	v_mfma_f32_16x16x32_bf16 v[122:125], v[154:157], v[242:245], v[122:125]
	s_setprio 0
	s_setprio 1
	v_mfma_f32_16x16x32_bf16 v[62:65], v[166:169], v[214:217], v[62:65]
	v_mfma_f32_16x16x32_bf16 v[58:61], v[206:209], v[214:217], v[58:61]
	v_mfma_f32_16x16x32_bf16 v[94:97], v[166:169], v[222:225], v[94:97]
	v_mfma_f32_16x16x32_bf16 v[90:93], v[206:209], v[222:225], v[90:93]
	v_mfma_f32_16x16x32_bf16 v[118:121], v[166:169], v[230:233], v[118:121]
	v_mfma_f32_16x16x32_bf16 v[114:117], v[206:209], v[230:233], v[114:117]
	v_mfma_f32_16x16x32_bf16 v[110:113], v[166:169], v[238:241], v[110:113]
	v_mfma_f32_16x16x32_bf16 v[106:109], v[206:209], v[238:241], v[106:109]
	v_mfma_f32_16x16x32_bf16 v[62:65], v[202:205], v[218:221], v[62:65]
	v_mfma_f32_16x16x32_bf16 v[58:61], v[210:213], v[218:221], v[58:61]
	v_mfma_f32_16x16x32_bf16 v[94:97], v[202:205], v[226:229], v[94:97]
	v_mfma_f32_16x16x32_bf16 v[90:93], v[210:213], v[226:229], v[90:93]
	v_mfma_f32_16x16x32_bf16 v[118:121], v[202:205], v[234:237], v[118:121]
	v_mfma_f32_16x16x32_bf16 v[114:117], v[210:213], v[234:237], v[114:117]
	v_mfma_f32_16x16x32_bf16 v[110:113], v[202:205], v[242:245], v[110:113]
	v_mfma_f32_16x16x32_bf16 v[106:109], v[210:213], v[242:245], v[106:109]
	s_setprio 0
	s_barrier
; #define PG8_STAGE(bufoff, gbase, voff) do { _Pragma("unroll") for (int _i = 0; _i < 2; ++_i) \
;         __builtin_amdgcn_global_load_lds((const unsigned*)((const char*)(gbase) + (voff)[_i]), (LAS unsigned*)(lds + (bufoff) + ldsw + _i * 8192), 16, 0, 0); } while (0)
; #define PG8_LDA(dst, b, h) do { _Pragma("unroll") for (int m = 0; m < 4; ++m) _Pragma("unroll") for (int k = 0; k < 2; ++k) dst[m][k] = *(const LAS bf16x8*)(lds + PG8_SA(b, h) + aoff + m * 2048 + k * 1024); } while (0)
; #define PG8_MMA(ai, bj, At, Bt) do { __builtin_amdgcn_s_setprio(1); _Pragma("unroll") for (int m = 0; m < 4; ++m) _Pragma("unroll") for (int n = 0; n < 2; ++n) _Pragma("unroll") for (int k = 0; k < 2; ++k) \
;         acc[ai][bj][m][n] = __builtin_amdgcn_mfma_f32_16x16x32_bf16(Bt[n][k], At[m][k], acc[ai][bj][m][n], 0, 0, 0); __builtin_amdgcn_s_setprio(0); } while (0)
; #define PG8_WAIT_V(n) asm volatile("s_waitcnt vmcnt(" #n ")" ::: "memory")
; #define PG8_WAIT_L(n) asm volatile("s_waitcnt lgkmcnt(" #n ")" ::: "memory")
; #define PG8_BAR __builtin_amdgcn_s_barrier()
; #define PG8_SCHED __builtin_amdgcn_sched_barrier(0)
; template <class Epi, class Sched, bool ALIGN_EPI = true>
; __device__ __forceinline__ void gemm_phase(LAS unsigned char* lds, const int wave_s, const int K, const Sched& S, const Epi& E) {
;     ...
;             PG8_LDA(At, 1, 1); PG8_STAGE(PG8_SB(1, 0), b3, voffB); PG8_STAGE(PG8_SB(1, 1), b3 + hstep, voffB); PG8_STAGE(PG8_SA(1, 0), a3, voffA);
;             PG8_WAIT_V(8); PG8_WAIT_L(0); PG8_BAR; PG8_MMA(1, 0, At, B0); PG8_MMA(1, 1, At, B1); PG8_BAR; PG8_SCHED;
;         }
	s_add_i32 s54, s83, s33
	v_lshl_add_u64 v[158:159], v[158:159], 0, s[22:23]
	s_mov_b32 m0, s54
	ds_read_b128 v[214:217], v191 offset:49152
	ds_read_b128 v[218:221], v191 offset:50176
	ds_read_b128 v[222:225], v191 offset:51200
	ds_read_b128 v[226:229], v191 offset:52224
	ds_read_b128 v[230:233], v191 offset:53248
	ds_read_b128 v[234:237], v191 offset:54272
	ds_read_b128 v[238:241], v191 offset:55296
	ds_read_b128 v[242:245], v191 offset:56320
	global_load_lds_dwordx4 v[158:159], off
	s_add_i32 m0, s54, 0x2000
	s_add_u32 s50, s50, 0x100080
	v_lshl_add_u64 v[158:159], v[160:161], 0, s[22:23]
	s_addc_u32 s51, s51, 0
	s_add_i32 s54, s84, s33
	global_load_lds_dwordx4 v[158:159], off
	v_lshl_add_u64 v[158:159], s[50:51], 0, v[0:1]
	s_mov_b32 m0, s54
	s_nop 0
	global_load_lds_dwordx4 v[158:159], off
	v_lshl_add_u64 v[158:159], s[50:51], 0, v[134:135]
	s_add_i32 m0, s54, 0x2000
	s_nop 0
	global_load_lds_dwordx4 v[158:159], off
	v_lshl_add_u64 v[158:159], v[162:163], 0, s[22:23]
	s_mov_b32 m0, s72
	s_nop 0
	global_load_lds_dwordx4 v[158:159], off
	v_lshl_add_u64 v[158:159], v[164:165], 0, s[22:23]
	s_mov_b32 m0, s73
	s_nop 0
	global_load_lds_dwordx4 v[158:159], off
	s_waitcnt vmcnt(8)
	s_waitcnt lgkmcnt(0)
	s_barrier
	s_setprio 1
	s_waitcnt lgkmcnt(0)
	v_mfma_f32_16x16x32_bf16 v[86:89], v[142:145], v[214:217], v[86:89]
	v_mfma_f32_16x16x32_bf16 v[82:85], v[150:153], v[214:217], v[82:85]
	v_mfma_f32_16x16x32_bf16 v[46:49], v[142:145], v[222:225], v[46:49]
	v_mfma_f32_16x16x32_bf16 v[42:45], v[150:153], v[222:225], v[42:45]
	v_mfma_f32_16x16x32_bf16 v[30:33], v[142:145], v[230:233], v[30:33]
	v_mfma_f32_16x16x32_bf16 v[26:29], v[150:153], v[230:233], v[26:29]
	v_mfma_f32_16x16x32_bf16 v[14:17], v[142:145], v[238:241], v[14:17]
	v_mfma_f32_16x16x32_bf16 v[10:13], v[150:153], v[238:241], v[10:13]
	v_mfma_f32_16x16x32_bf16 v[86:89], v[146:149], v[218:221], v[86:89]
	v_mfma_f32_16x16x32_bf16 v[82:85], v[154:157], v[218:221], v[82:85]
	v_mfma_f32_16x16x32_bf16 v[46:49], v[146:149], v[226:229], v[46:49]
	v_mfma_f32_16x16x32_bf16 v[42:45], v[154:157], v[226:229], v[42:45]
	v_mfma_f32_16x16x32_bf16 v[30:33], v[146:149], v[234:237], v[30:33]
	v_mfma_f32_16x16x32_bf16 v[26:29], v[154:157], v[234:237], v[26:29]
	v_mfma_f32_16x16x32_bf16 v[14:17], v[146:149], v[242:245], v[14:17]
	v_mfma_f32_16x16x32_bf16 v[10:13], v[154:157], v[242:245], v[10:13]
	s_setprio 0
	s_setprio 1
	v_mfma_f32_16x16x32_bf16 v[70:73], v[166:169], v[214:217], v[70:73]
	v_mfma_f32_16x16x32_bf16 v[66:69], v[206:209], v[214:217], v[66:69]
	v_mfma_f32_16x16x32_bf16 v[38:41], v[166:169], v[222:225], v[38:41]
	v_mfma_f32_16x16x32_bf16 v[34:37], v[206:209], v[222:225], v[34:37]
	v_mfma_f32_16x16x32_bf16 v[22:25], v[166:169], v[230:233], v[22:25]
	v_mfma_f32_16x16x32_bf16 v[18:21], v[206:209], v[230:233], v[18:21]
	v_mfma_f32_16x16x32_bf16 v[6:9], v[166:169], v[238:241], v[6:9]
	v_mfma_f32_16x16x32_bf16 v[2:5], v[206:209], v[238:241], v[2:5]
	v_mfma_f32_16x16x32_bf16 v[70:73], v[202:205], v[218:221], v[70:73]
	v_mfma_f32_16x16x32_bf16 v[66:69], v[210:213], v[218:221], v[66:69]
	v_mfma_f32_16x16x32_bf16 v[38:41], v[202:205], v[226:229], v[38:41]
	v_mfma_f32_16x16x32_bf16 v[34:37], v[210:213], v[226:229], v[34:37]
	v_mfma_f32_16x16x32_bf16 v[22:25], v[202:205], v[234:237], v[22:25]
	v_mfma_f32_16x16x32_bf16 v[18:21], v[210:213], v[234:237], v[18:21]
	v_mfma_f32_16x16x32_bf16 v[6:9], v[202:205], v[242:245], v[6:9]
	v_mfma_f32_16x16x32_bf16 v[2:5], v[210:213], v[242:245], v[2:5]
	s_setprio 0
	s_barrier
	s_add_i32 s81, s81, 2
	s_add_u32 s12, s12, 0x100
	s_addc_u32 s13, s13, 0
	s_add_u32 s79, s79, 0x100
	s_addc_u32 s80, s80, 0
	s_cmp_gt_u32 s81, 61

; #define PG8_STAGE(bufoff, gbase, voff) do { _Pragma("unroll") for (int _i = 0; _i < 2; ++_i) \
;         __builtin_amdgcn_global_load_lds((const unsigned*)((const char*)(gbase) + (voff)[_i]), (LAS unsigned*)(lds + (bufoff) + ldsw + _i * 8192), 16, 0, 0); } while (0)
; #define PG8_LDA(dst, b, h) do { _Pragma("unroll") for (int m = 0; m < 4; ++m) _Pragma("unroll") for (int k = 0; k < 2; ++k) dst[m][k] = *(const LAS bf16x8*)(lds + PG8_SA(b, h) + aoff + m * 2048 + k * 1024); } while (0)
; #define PG8_LDB(dst, b, h) do { _Pragma("unroll") for (int n = 0; n < 2; ++n) _Pragma("unroll") for (int k = 0; k < 2; ++k) dst[n][k] = *(const LAS bf16x8*)(lds + PG8_SB(b, h) + boff + n * 2048 + k * 1024); } while (0)
; #define PG8_BAR __builtin_amdgcn_s_barrier()
; template <class Epi, class Sched, bool ALIGN_EPI = true>
; __device__ __forceinline__ void gemm_phase(LAS unsigned char* lds, const int wave_s, const int K, const Sched& S, const Epi& E) {
;     ...
;     PG8_STAGE(PG8_SB(0, 0), cB, voffB); PG8_STAGE(PG8_SB(0, 1), cB + hstep, voffB); PG8_STAGE(PG8_SA(0, 0), cA, voffA); PG8_STAGE(PG8_SA(0, 1), cA + hstep, voffA);
;     if (wr == 1) PG8_BAR;
;     PG8_WAIT_V(2); PG8_BAR;
;     PG8_STAGE(PG8_SB(1, 0), cB + kstep, voffB); PG8_STAGE(PG8_SA(1, 0), cA + kstep, voffA); PG8_STAGE(PG8_SB(1, 1), cB + hstep + kstep, voffB);
;     PG8_WAIT_V(6); PG8_BAR;
;     for (;;) {
;         const bool has_next = S.next(ui + 1, nxt);
;         const char* nA = has_next ? S.aptr(nxt) : cA; const char* nB = has_next ? S.bptr(nxt) : cB;
;         for (int t = 0; t < nt; t += 2) {
;             const bool last = (t == nt - 2);
;             const char* a1 = cA + (size_t)(t + 1) * kstep;
;             const char* a2 = last ? nA : cA + (size_t)(t + 2) * kstep; const char* b2 = last ? nB : cB + (size_t)(t + 2) * kstep;
;             const char* a3 = a2 + kstep; const char* b3 = b2 + kstep;
;             PG8_LDB(B0, 0, 0); PG8_LDB(B1, 0, 1); PG8_SCHED; PG8_LDA(At, 0, 0); PG8_STAGE(PG8_SA(1, 1), a1 + hstep, voffA);
;             PG8_WAIT_V(8); PG8_WAIT_L(0); PG8_BAR; PG8_MMA(0, 0, At, B0); PG8_MMA(0, 1, At, B1); PG8_BAR; PG8_SCHED;
;             PG8_LDA(At, 0, 1); PG8_STAGE(PG8_SB(0, 0), b2, voffB); PG8_STAGE(PG8_SB(0, 1), b2 + hstep, voffB); PG8_STAGE(PG8_SA(0, 0), a2, voffA);
;             PG8_WAIT_V(8); PG8_WAIT_L(0); PG8_BAR; PG8_MMA(1, 0, At, B0); PG8_MMA(1, 1, At, B1); PG8_BAR; PG8_SCHED;
.LBB0_159:
	s_ashr_i32 s35, s34, 31
	s_lshl_b64 s[44:45], s[34:35], 19
	s_add_u32 s44, s4, s44
	s_addc_u32 s45, s5, s45
	s_and_b64 s[46:47], s[42:43], exec
	s_cselect_b32 s35, s45, s49
	s_cselect_b32 s56, s44, s48
	s_ashr_i32 s15, s14, 31
	s_lshl_b64 s[46:47], s[14:15], 19
	s_add_u32 s46, s7, s46
	s_addc_u32 s47, s16, s47
	s_and_b64 s[52:53], s[42:43], exec
	s_cselect_b32 s15, s47, s51
	s_cselect_b32 s57, s46, s50
	s_add_u32 s48, s48, 0x40080
	s_addc_u32 s49, s49, 0
	s_add_u32 s60, s50, 0x100
	s_addc_u32 s61, s51, 0
	s_mov_b32 s62, -2
	s_add_u32 s50, s48, 0xfffc0080
	s_addc_u32 s51, s49, -1
	s_add_i32 s63, 0, 0x10000
	s_cmp_eq_u32 s62, 12
	s_cselect_b32 s53, s35, s51
	s_cselect_b32 s52, s56, s50
	v_add_u32_e32 v140, s63, v143
	s_cselect_b32 s51, s15, s61
	s_cselect_b32 s50, s57, s60
	s_add_i32 s68, 0, 0x14000
	ds_read_b128 v[146:149], v140
	ds_read_b128 v[150:153], v140 offset:1024
	ds_read_b128 v[154:157], v140 offset:2048
	ds_read_b128 v[166:169], v140 offset:3072
	v_add_u32_e32 v140, s68, v143
	ds_read_b128 v[170:173], v140
	ds_read_b128 v[174:177], v140 offset:1024
	ds_read_b128 v[178:181], v140 offset:2048
	ds_read_b128 v[182:185], v140 offset:3072
	v_lshl_add_u64 v[140:141], s[48:49], 0, v[136:137]
	s_add_i32 m0, s18, 0xc000
	ds_read_b128 v[186:189], v145
	ds_read_b128 v[202:205], v145 offset:1024
	ds_read_b128 v[206:209], v145 offset:2048
	ds_read_b128 v[210:213], v145 offset:3072
	ds_read_b128 v[214:217], v145 offset:4096
	ds_read_b128 v[218:221], v145 offset:5120
	ds_read_b128 v[222:225], v145 offset:6144
	ds_read_b128 v[226:229], v145 offset:7168
	global_load_lds_dwordx4 v[140:141], off
	v_lshl_add_u64 v[140:141], s[48:49], 0, v[138:139]
	s_add_i32 m0, s18, 0xe000
	s_nop 0
	global_load_lds_dwordx4 v[140:141], off
	s_waitcnt vmcnt(8)
	s_waitcnt lgkmcnt(0)
	s_barrier
	s_setprio 1
	s_waitcnt lgkmcnt(0)
	v_mfma_f32_16x16x32_bf16 v[126:129], v[146:149], v[186:189], 0
	v_mfma_f32_16x16x32_bf16 v[122:125], v[154:157], v[186:189], 0
	v_mfma_f32_16x16x32_bf16 v[110:113], v[146:149], v[206:209], 0
	v_mfma_f32_16x16x32_bf16 v[106:109], v[154:157], v[206:209], 0
	v_mfma_f32_16x16x32_bf16 v[94:97], v[146:149], v[214:217], 0
	v_mfma_f32_16x16x32_bf16 v[90:93], v[154:157], v[214:217], 0
	v_mfma_f32_16x16x32_bf16 v[78:81], v[146:149], v[222:225], 0
	v_mfma_f32_16x16x32_bf16 v[74:77], v[154:157], v[222:225], 0
	v_mfma_f32_16x16x32_bf16 v[126:129], v[150:153], v[202:205], v[126:129]
	v_mfma_f32_16x16x32_bf16 v[122:125], v[166:169], v[202:205], v[122:125]
	v_mfma_f32_16x16x32_bf16 v[110:113], v[150:153], v[210:213], v[110:113]
	v_mfma_f32_16x16x32_bf16 v[106:109], v[166:169], v[210:213], v[106:109]
	v_mfma_f32_16x16x32_bf16 v[94:97], v[150:153], v[218:221], v[94:97]
	v_mfma_f32_16x16x32_bf16 v[90:93], v[166:169], v[218:221], v[90:93]
	v_mfma_f32_16x16x32_bf16 v[78:81], v[150:153], v[226:229], v[78:81]
	v_mfma_f32_16x16x32_bf16 v[74:77], v[166:169], v[226:229], v[74:77]
	s_setprio 0
	s_setprio 1
	v_mfma_f32_16x16x32_bf16 v[118:121], v[170:173], v[186:189], 0
	v_mfma_f32_16x16x32_bf16 v[114:117], v[178:181], v[186:189], 0
	v_mfma_f32_16x16x32_bf16 v[102:105], v[170:173], v[206:209], 0
	v_mfma_f32_16x16x32_bf16 v[98:101], v[178:181], v[206:209], 0
	v_mfma_f32_16x16x32_bf16 v[86:89], v[170:173], v[214:217], 0
	v_mfma_f32_16x16x32_bf16 v[82:85], v[178:181], v[214:217], 0
	v_mfma_f32_16x16x32_bf16 v[70:73], v[170:173], v[222:225], 0
	v_mfma_f32_16x16x32_bf16 v[66:69], v[178:181], v[222:225], 0
	v_mfma_f32_16x16x32_bf16 v[118:121], v[174:177], v[202:205], v[118:121]
	v_mfma_f32_16x16x32_bf16 v[114:117], v[182:185], v[202:205], v[114:117]
	v_mfma_f32_16x16x32_bf16 v[102:105], v[174:177], v[210:213], v[102:105]
	v_mfma_f32_16x16x32_bf16 v[98:101], v[182:185], v[210:213], v[98:101]
	v_mfma_f32_16x16x32_bf16 v[86:89], v[174:177], v[218:221], v[86:89]
	v_mfma_f32_16x16x32_bf16 v[82:85], v[182:185], v[218:221], v[82:85]
	v_mfma_f32_16x16x32_bf16 v[70:73], v[174:177], v[226:229], v[70:73]
	v_mfma_f32_16x16x32_bf16 v[66:69], v[182:185], v[226:229], v[66:69]
	s_setprio 0
	s_barrier
	s_add_i32 s63, s63, s33
	v_lshl_add_u64 v[140:141], s[50:51], 0, v[0:1]
	s_mov_b32 m0, s63
	ds_read_b128 v[186:189], v145 offset:16384
	ds_read_b128 v[202:205], v145 offset:17408
	ds_read_b128 v[206:209], v145 offset:18432
	ds_read_b128 v[210:213], v145 offset:19456
	ds_read_b128 v[214:217], v145 offset:20480
	ds_read_b128 v[218:221], v145 offset:21504
	ds_read_b128 v[222:225], v145 offset:22528
	ds_read_b128 v[226:229], v145 offset:23552
	global_load_lds_dwordx4 v[140:141], off
	s_add_i32 m0, s63, 0x2000
	s_add_u32 s64, s50, 0x40000
	v_lshl_add_u64 v[158:159], s[50:51], 0, v[130:131]
	s_addc_u32 s65, s51, 0
	s_add_i32 s63, s68, s33
	global_load_lds_dwordx4 v[158:159], off
	v_lshl_add_u64 v[160:161], s[64:65], 0, v[0:1]
	s_mov_b32 m0, s63
	v_lshl_add_u64 v[162:163], s[52:53], 0, v[132:133]
	global_load_lds_dwordx4 v[160:161], off
	v_lshl_add_u64 v[160:161], s[64:65], 0, v[130:131]
	s_add_i32 m0, s63, 0x2000
	s_nop 0
	global_load_lds_dwordx4 v[160:161], off
	v_lshl_add_u64 v[160:161], s[52:53], 0, v[134:135]
	s_mov_b32 m0, s18
	s_nop 0
	global_load_lds_dwordx4 v[160:161], off
	s_mov_b32 m0, s19
	s_nop 0
	global_load_lds_dwordx4 v[162:163], off
	s_waitcnt vmcnt(8)
	s_waitcnt lgkmcnt(0)
	s_barrier
; #define PG8_STAGE(bufoff, gbase, voff) do { _Pragma("unroll") for (int _i = 0; _i < 2; ++_i) \
;         __builtin_amdgcn_global_load_lds((const unsigned*)((const char*)(gbase) + (voff)[_i]), (LAS unsigned*)(lds + (bufoff) + ldsw + _i * 8192), 16, 0, 0); } while (0)
; #define PG8_LDA(dst, b, h) do { _Pragma("unroll") for (int m = 0; m < 4; ++m) _Pragma("unroll") for (int k = 0; k < 2; ++k) dst[m][k] = *(const LAS bf16x8*)(lds + PG8_SA(b, h) + aoff + m * 2048 + k * 1024); } while (0)
; #define PG8_LDB(dst, b, h) do { _Pragma("unroll") for (int n = 0; n < 2; ++n) _Pragma("unroll") for (int k = 0; k < 2; ++k) dst[n][k] = *(const LAS bf16x8*)(lds + PG8_SB(b, h) + boff + n * 2048 + k * 1024); } while (0)
; #define PG8_MMA(ai, bj, At, Bt) do { __builtin_amdgcn_s_setprio(1); _Pragma("unroll") for (int m = 0; m < 4; ++m) _Pragma("unroll") for (int n = 0; n < 2; ++n) _Pragma("unroll") for (int k = 0; k < 2; ++k) \
;         acc[ai][bj][m][n] = __builtin_amdgcn_mfma_f32_16x16x32_bf16(Bt[n][k], At[m][k], acc[ai][bj][m][n], 0, 0, 0); __builtin_amdgcn_s_setprio(0); } while (0)
; #define PG8_WAIT_V(n) asm volatile("s_waitcnt vmcnt(" #n ")" ::: "memory")
; #define PG8_WAIT_L(n) asm volatile("s_waitcnt lgkmcnt(" #n ")" ::: "memory")
; #define PG8_BAR __builtin_amdgcn_s_barrier()
; #define PG8_SCHED __builtin_amdgcn_sched_barrier(0)
; template <class Epi, class Sched, bool ALIGN_EPI = true>
; __device__ __forceinline__ void gemm_phase(LAS unsigned char* lds, const int wave_s, const int K, const Sched& S, const Epi& E) {
;     ...
;             PG8_WAIT_V(8); PG8_WAIT_L(0); PG8_BAR; PG8_MMA(1, 0, At, B0); PG8_MMA(1, 1, At, B1); PG8_BAR; PG8_SCHED;
;             PG8_LDB(B0, 1, 0); PG8_LDB(B1, 1, 1); PG8_SCHED; PG8_LDA(At, 1, 0); PG8_STAGE(PG8_SA(0, 1), a2 + hstep, voffA);
;             PG8_WAIT_V(8); PG8_WAIT_L(0); PG8_BAR; PG8_MMA(0, 0, At, B0); PG8_MMA(0, 1, At, B1); PG8_BAR; PG8_SCHED;
;             PG8_LDA(At, 1, 1); PG8_STAGE(PG8_SB(1, 0), b3, voffB); PG8_STAGE(PG8_SB(1, 1), b3 + hstep, voffB); PG8_STAGE(PG8_SA(1, 0), a3, voffA);
	s_setprio 1
	s_waitcnt lgkmcnt(0)
	v_mfma_f32_16x16x32_bf16 v[62:65], v[146:149], v[186:189], 0
	v_mfma_f32_16x16x32_bf16 v[58:61], v[154:157], v[186:189], 0
	v_mfma_f32_16x16x32_bf16 v[46:49], v[146:149], v[206:209], 0
	v_mfma_f32_16x16x32_bf16 v[42:45], v[154:157], v[206:209], 0
	v_mfma_f32_16x16x32_bf16 v[30:33], v[146:149], v[214:217], 0
	v_mfma_f32_16x16x32_bf16 v[26:29], v[154:157], v[214:217], 0
	v_mfma_f32_16x16x32_bf16 v[14:17], v[146:149], v[222:225], 0
	v_mfma_f32_16x16x32_bf16 v[10:13], v[154:157], v[222:225], 0
	v_mfma_f32_16x16x32_bf16 v[62:65], v[150:153], v[202:205], v[62:65]
	v_mfma_f32_16x16x32_bf16 v[58:61], v[166:169], v[202:205], v[58:61]
	v_mfma_f32_16x16x32_bf16 v[46:49], v[150:153], v[210:213], v[46:49]
	v_mfma_f32_16x16x32_bf16 v[42:45], v[166:169], v[210:213], v[42:45]
	v_mfma_f32_16x16x32_bf16 v[30:33], v[150:153], v[218:221], v[30:33]
	v_mfma_f32_16x16x32_bf16 v[26:29], v[166:169], v[218:221], v[26:29]
	v_mfma_f32_16x16x32_bf16 v[14:17], v[150:153], v[226:229], v[14:17]
	v_mfma_f32_16x16x32_bf16 v[10:13], v[166:169], v[226:229], v[10:13]
	s_setprio 0
	s_setprio 1
	v_mfma_f32_16x16x32_bf16 v[54:57], v[170:173], v[186:189], 0
	v_mfma_f32_16x16x32_bf16 v[50:53], v[178:181], v[186:189], 0
	v_mfma_f32_16x16x32_bf16 v[38:41], v[170:173], v[206:209], 0
	v_mfma_f32_16x16x32_bf16 v[34:37], v[178:181], v[206:209], 0
	v_mfma_f32_16x16x32_bf16 v[22:25], v[170:173], v[214:217], 0
	v_mfma_f32_16x16x32_bf16 v[18:21], v[178:181], v[214:217], 0
	v_mfma_f32_16x16x32_bf16 v[6:9], v[170:173], v[222:225], 0
	v_mfma_f32_16x16x32_bf16 v[2:5], v[178:181], v[222:225], 0
	v_mfma_f32_16x16x32_bf16 v[54:57], v[174:177], v[202:205], v[54:57]
	v_mfma_f32_16x16x32_bf16 v[50:53], v[182:185], v[202:205], v[50:53]
	v_mfma_f32_16x16x32_bf16 v[38:41], v[174:177], v[210:213], v[38:41]
	v_mfma_f32_16x16x32_bf16 v[34:37], v[182:185], v[210:213], v[34:37]
	v_mfma_f32_16x16x32_bf16 v[22:25], v[174:177], v[218:221], v[22:25]
	v_mfma_f32_16x16x32_bf16 v[18:21], v[182:185], v[218:221], v[18:21]
	v_mfma_f32_16x16x32_bf16 v[6:9], v[174:177], v[226:229], v[6:9]
	v_mfma_f32_16x16x32_bf16 v[2:5], v[182:185], v[226:229], v[2:5]
	s_setprio 0
	s_barrier
	s_add_i32 s63, 0, 0x18000
	v_add_u32_e32 v164, s63, v143
	s_add_i32 s64, 0, 0x1c000
	ds_read_b128 v[146:149], v164
	ds_read_b128 v[150:153], v164 offset:1024
	ds_read_b128 v[154:157], v164 offset:2048
	ds_read_b128 v[166:169], v164 offset:3072
	v_add_u32_e32 v164, s64, v143
	ds_read_b128 v[170:173], v164
	ds_read_b128 v[174:177], v164 offset:1024
	ds_read_b128 v[178:181], v164 offset:2048
	ds_read_b128 v[182:185], v164 offset:3072
	s_add_u32 s52, s52, 0x40000
	s_addc_u32 s53, s53, 0
	s_mov_b32 m0, s20
	v_lshl_add_u64 v[164:165], s[52:53], 0, v[134:135]
	ds_read_b128 v[186:189], v145 offset:32768
	ds_read_b128 v[202:205], v145 offset:33792
	ds_read_b128 v[206:209], v145 offset:34816
	ds_read_b128 v[210:213], v145 offset:35840
	ds_read_b128 v[214:217], v145 offset:36864
	ds_read_b128 v[218:221], v145 offset:37888
	ds_read_b128 v[222:225], v145 offset:38912
	ds_read_b128 v[226:229], v145 offset:39936
	global_load_lds_dwordx4 v[164:165], off
	v_lshl_add_u64 v[164:165], s[52:53], 0, v[132:133]
	s_mov_b32 m0, s21
	s_nop 0
	global_load_lds_dwordx4 v[164:165], off
	s_waitcnt vmcnt(8)
	s_waitcnt lgkmcnt(0)
	s_barrier
	s_setprio 1
	s_waitcnt lgkmcnt(0)
	v_mfma_f32_16x16x32_bf16 v[126:129], v[146:149], v[186:189], v[126:129]
	v_mfma_f32_16x16x32_bf16 v[122:125], v[154:157], v[186:189], v[122:125]
	v_mfma_f32_16x16x32_bf16 v[110:113], v[146:149], v[206:209], v[110:113]
	v_mfma_f32_16x16x32_bf16 v[106:109], v[154:157], v[206:209], v[106:109]
	v_mfma_f32_16x16x32_bf16 v[94:97], v[146:149], v[214:217], v[94:97]
	v_mfma_f32_16x16x32_bf16 v[90:93], v[154:157], v[214:217], v[90:93]
	v_mfma_f32_16x16x32_bf16 v[78:81], v[146:149], v[222:225], v[78:81]
	v_mfma_f32_16x16x32_bf16 v[74:77], v[154:157], v[222:225], v[74:77]
	v_mfma_f32_16x16x32_bf16 v[126:129], v[150:153], v[202:205], v[126:129]
	v_mfma_f32_16x16x32_bf16 v[122:125], v[166:169], v[202:205], v[122:125]
	v_mfma_f32_16x16x32_bf16 v[110:113], v[150:153], v[210:213], v[110:113]
	v_mfma_f32_16x16x32_bf16 v[106:109], v[166:169], v[210:213], v[106:109]
	v_mfma_f32_16x16x32_bf16 v[94:97], v[150:153], v[218:221], v[94:97]
	v_mfma_f32_16x16x32_bf16 v[90:93], v[166:169], v[218:221], v[90:93]
	v_mfma_f32_16x16x32_bf16 v[78:81], v[150:153], v[226:229], v[78:81]
	v_mfma_f32_16x16x32_bf16 v[74:77], v[166:169], v[226:229], v[74:77]
	s_setprio 0
	s_setprio 1
	v_mfma_f32_16x16x32_bf16 v[118:121], v[170:173], v[186:189], v[118:121]
	v_mfma_f32_16x16x32_bf16 v[114:117], v[178:181], v[186:189], v[114:117]
	v_mfma_f32_16x16x32_bf16 v[102:105], v[170:173], v[206:209], v[102:105]
	v_mfma_f32_16x16x32_bf16 v[98:101], v[178:181], v[206:209], v[98:101]
	v_mfma_f32_16x16x32_bf16 v[86:89], v[170:173], v[214:217], v[86:89]
	v_mfma_f32_16x16x32_bf16 v[82:85], v[178:181], v[214:217], v[82:85]
	v_mfma_f32_16x16x32_bf16 v[70:73], v[170:173], v[222:225], v[70:73]
	v_mfma_f32_16x16x32_bf16 v[66:69], v[178:181], v[222:225], v[66:69]
	v_mfma_f32_16x16x32_bf16 v[118:121], v[174:177], v[202:205], v[118:121]
	v_mfma_f32_16x16x32_bf16 v[114:117], v[182:185], v[202:205], v[114:117]
	v_mfma_f32_16x16x32_bf16 v[102:105], v[174:177], v[210:213], v[102:105]
	v_mfma_f32_16x16x32_bf16 v[98:101], v[182:185], v[210:213], v[98:101]
	v_mfma_f32_16x16x32_bf16 v[86:89], v[174:177], v[218:221], v[86:89]
	v_mfma_f32_16x16x32_bf16 v[82:85], v[182:185], v[218:221], v[82:85]
	v_mfma_f32_16x16x32_bf16 v[70:73], v[174:177], v[226:229], v[70:73]
	v_mfma_f32_16x16x32_bf16 v[66:69], v[182:185], v[226:229], v[66:69]
	s_setprio 0
	s_barrier
; #define PG8_STAGE(bufoff, gbase, voff) do { _Pragma("unroll") for (int _i = 0; _i < 2; ++_i) \
;         __builtin_amdgcn_global_load_lds((const unsigned*)((const char*)(gbase) + (voff)[_i]), (LAS unsigned*)(lds + (bufoff) + ldsw + _i * 8192), 16, 0, 0); } while (0)
; #define PG8_LDA(dst, b, h) do { _Pragma("unroll") for (int m = 0; m < 4; ++m) _Pragma("unroll") for (int k = 0; k < 2; ++k) dst[m][k] = *(const LAS bf16x8*)(lds + PG8_SA(b, h) + aoff + m * 2048 + k * 1024); } while (0)
; #define PG8_MMA(ai, bj, At, Bt) do { __builtin_amdgcn_s_setprio(1); _Pragma("unroll") for (int m = 0; m < 4; ++m) _Pragma("unroll") for (int n = 0; n < 2; ++n) _Pragma("unroll") for (int k = 0; k < 2; ++k) \
;         acc[ai][bj][m][n] = __builtin_amdgcn_mfma_f32_16x16x32_bf16(Bt[n][k], At[m][k], acc[ai][bj][m][n], 0, 0, 0); __builtin_amdgcn_s_setprio(0); } while (0)
; #define PG8_WAIT_V(n) asm volatile("s_waitcnt vmcnt(" #n ")" ::: "memory")
; #define PG8_WAIT_L(n) asm volatile("s_waitcnt lgkmcnt(" #n ")" ::: "memory")
; #define PG8_BAR __builtin_amdgcn_s_barrier()
; #define PG8_SCHED __builtin_amdgcn_sched_barrier(0)
; template <class Epi, class Sched, bool ALIGN_EPI = true>
; __device__ __forceinline__ void gemm_phase(LAS unsigned char* lds, const int wave_s, const int K, const Sched& S, const Epi& E) {
;     ...
;             PG8_LDA(At, 1, 1); PG8_STAGE(PG8_SB(1, 0), b3, voffB); PG8_STAGE(PG8_SB(1, 1), b3 + hstep, voffB); PG8_STAGE(PG8_SA(1, 0), a3, voffA);
;             PG8_WAIT_V(8); PG8_WAIT_L(0); PG8_BAR; PG8_MMA(1, 0, At, B0); PG8_MMA(1, 1, At, B1); PG8_BAR; PG8_SCHED;
;         }
	s_add_i32 s52, s63, s33
	v_lshl_add_u64 v[140:141], v[140:141], 0, s[22:23]
	s_mov_b32 m0, s52
	ds_read_b128 v[186:189], v145 offset:49152
	ds_read_b128 v[202:205], v145 offset:50176
	ds_read_b128 v[206:209], v145 offset:51200
	ds_read_b128 v[210:213], v145 offset:52224
	ds_read_b128 v[214:217], v145 offset:53248
	ds_read_b128 v[218:221], v145 offset:54272
	ds_read_b128 v[222:225], v145 offset:55296
	ds_read_b128 v[226:229], v145 offset:56320
	global_load_lds_dwordx4 v[140:141], off
	s_add_i32 m0, s52, 0x2000
	s_add_u32 s50, s50, 0x40080
	v_lshl_add_u64 v[140:141], v[158:159], 0, s[22:23]
	s_addc_u32 s51, s51, 0
	s_add_i32 s52, s64, s33
	global_load_lds_dwordx4 v[140:141], off
	v_lshl_add_u64 v[140:141], s[50:51], 0, v[0:1]
	s_mov_b32 m0, s52
	s_nop 0
	global_load_lds_dwordx4 v[140:141], off
	v_lshl_add_u64 v[140:141], s[50:51], 0, v[130:131]
	s_add_i32 m0, s52, 0x2000
	s_nop 0
	global_load_lds_dwordx4 v[140:141], off
	v_lshl_add_u64 v[140:141], v[160:161], 0, s[22:23]
	s_mov_b32 m0, s28
	s_nop 0
	global_load_lds_dwordx4 v[140:141], off
	v_lshl_add_u64 v[140:141], v[162:163], 0, s[22:23]
	s_mov_b32 m0, s30
	s_nop 0
	global_load_lds_dwordx4 v[140:141], off
	s_waitcnt vmcnt(8)
	s_waitcnt lgkmcnt(0)
	s_barrier
	s_setprio 1
	s_waitcnt lgkmcnt(0)
	v_mfma_f32_16x16x32_bf16 v[62:65], v[146:149], v[186:189], v[62:65]
	v_mfma_f32_16x16x32_bf16 v[58:61], v[154:157], v[186:189], v[58:61]
	v_mfma_f32_16x16x32_bf16 v[46:49], v[146:149], v[206:209], v[46:49]
	v_mfma_f32_16x16x32_bf16 v[42:45], v[154:157], v[206:209], v[42:45]
	v_mfma_f32_16x16x32_bf16 v[30:33], v[146:149], v[214:217], v[30:33]
	v_mfma_f32_16x16x32_bf16 v[26:29], v[154:157], v[214:217], v[26:29]
	v_mfma_f32_16x16x32_bf16 v[14:17], v[146:149], v[222:225], v[14:17]
	v_mfma_f32_16x16x32_bf16 v[10:13], v[154:157], v[222:225], v[10:13]
	v_mfma_f32_16x16x32_bf16 v[62:65], v[150:153], v[202:205], v[62:65]
	v_mfma_f32_16x16x32_bf16 v[58:61], v[166:169], v[202:205], v[58:61]
	v_mfma_f32_16x16x32_bf16 v[46:49], v[150:153], v[210:213], v[46:49]
	v_mfma_f32_16x16x32_bf16 v[42:45], v[166:169], v[210:213], v[42:45]
	v_mfma_f32_16x16x32_bf16 v[30:33], v[150:153], v[218:221], v[30:33]
	v_mfma_f32_16x16x32_bf16 v[26:29], v[166:169], v[218:221], v[26:29]
	v_mfma_f32_16x16x32_bf16 v[14:17], v[150:153], v[226:229], v[14:17]
	v_mfma_f32_16x16x32_bf16 v[10:13], v[166:169], v[226:229], v[10:13]
	s_setprio 0
	s_setprio 1
	v_mfma_f32_16x16x32_bf16 v[54:57], v[170:173], v[186:189], v[54:57]
	v_mfma_f32_16x16x32_bf16 v[50:53], v[178:181], v[186:189], v[50:53]
	v_mfma_f32_16x16x32_bf16 v[38:41], v[170:173], v[206:209], v[38:41]
	v_mfma_f32_16x16x32_bf16 v[34:37], v[178:181], v[206:209], v[34:37]
	v_mfma_f32_16x16x32_bf16 v[22:25], v[170:173], v[214:217], v[22:25]
	v_mfma_f32_16x16x32_bf16 v[18:21], v[178:181], v[214:217], v[18:21]
	v_mfma_f32_16x16x32_bf16 v[6:9], v[170:173], v[222:225], v[6:9]
	v_mfma_f32_16x16x32_bf16 v[2:5], v[178:181], v[222:225], v[2:5]
	v_mfma_f32_16x16x32_bf16 v[54:57], v[174:177], v[202:205], v[54:57]
	v_mfma_f32_16x16x32_bf16 v[50:53], v[182:185], v[202:205], v[50:53]
	v_mfma_f32_16x16x32_bf16 v[38:41], v[174:177], v[210:213], v[38:41]
	v_mfma_f32_16x16x32_bf16 v[34:37], v[182:185], v[210:213], v[34:37]
	v_mfma_f32_16x16x32_bf16 v[22:25], v[174:177], v[218:221], v[22:25]
	v_mfma_f32_16x16x32_bf16 v[18:21], v[182:185], v[218:221], v[18:21]
	v_mfma_f32_16x16x32_bf16 v[6:9], v[174:177], v[226:229], v[6:9]
	v_mfma_f32_16x16x32_bf16 v[2:5], v[182:185], v[226:229], v[2:5]
	s_setprio 0
	s_barrier
	s_add_i32 s62, s62, 2
	s_add_u32 s48, s48, 0x100
	s_addc_u32 s49, s49, 0
	s_add_u32 s60, s60, 0x100
	s_addc_u32 s61, s61, 0
	s_cmp_gt_u32 s62, 13

; #define PG8_STAGE(bufoff, gbase, voff) do { _Pragma("unroll") for (int _i = 0; _i < 2; ++_i) \
;         __builtin_amdgcn_global_load_lds((const unsigned*)((const char*)(gbase) + (voff)[_i]), (LAS unsigned*)(lds + (bufoff) + ldsw + _i * 8192), 16, 0, 0); } while (0)
; #define PG8_LDA(dst, b, h) do { _Pragma("unroll") for (int m = 0; m < 4; ++m) _Pragma("unroll") for (int k = 0; k < 2; ++k) dst[m][k] = *(const LAS bf16x8*)(lds + PG8_SA(b, h) + aoff + m * 2048 + k * 1024); } while (0)
; #define PG8_LDB(dst, b, h) do { _Pragma("unroll") for (int n = 0; n < 2; ++n) _Pragma("unroll") for (int k = 0; k < 2; ++k) dst[n][k] = *(const LAS bf16x8*)(lds + PG8_SB(b, h) + boff + n * 2048 + k * 1024); } while (0)
; #define PG8_BAR __builtin_amdgcn_s_barrier()
; template <class Epi, class Sched, bool ALIGN_EPI = true>
; __device__ __forceinline__ void gemm_phase(LAS unsigned char* lds, const int wave_s, const int K, const Sched& S, const Epi& E) {
;     ...
;     PG8_STAGE(PG8_SB(0, 0), cB, voffB); PG8_STAGE(PG8_SB(0, 1), cB + hstep, voffB); PG8_STAGE(PG8_SA(0, 0), cA, voffA); PG8_STAGE(PG8_SA(0, 1), cA + hstep, voffA);
;     if (wr == 1) PG8_BAR;
;     PG8_WAIT_V(2); PG8_BAR;
;     PG8_STAGE(PG8_SB(1, 0), cB + kstep, voffB); PG8_STAGE(PG8_SA(1, 0), cA + kstep, voffA); PG8_STAGE(PG8_SB(1, 1), cB + hstep + kstep, voffB);
;     PG8_WAIT_V(6); PG8_BAR;
;     for (;;) {
;         const bool has_next = S.next(ui + 1, nxt);
;         const char* nA = has_next ? S.aptr(nxt) : cA; const char* nB = has_next ? S.bptr(nxt) : cB;
;         for (int t = 0; t < nt; t += 2) {
;             const bool last = (t == nt - 2);
;             const char* a1 = cA + (size_t)(t + 1) * kstep;
;             const char* a2 = last ? nA : cA + (size_t)(t + 2) * kstep; const char* b2 = last ? nB : cB + (size_t)(t + 2) * kstep;
;             const char* a3 = a2 + kstep; const char* b3 = b2 + kstep;
;             PG8_LDB(B0, 0, 0); PG8_LDB(B1, 0, 1); PG8_SCHED; PG8_LDA(At, 0, 0); PG8_STAGE(PG8_SA(1, 1), a1 + hstep, voffA);
;             PG8_WAIT_V(8); PG8_WAIT_L(0); PG8_BAR; PG8_MMA(0, 0, At, B0); PG8_MMA(0, 1, At, B1); PG8_BAR; PG8_SCHED;
;             PG8_LDA(At, 0, 1); PG8_STAGE(PG8_SB(0, 0), b2, voffB); PG8_STAGE(PG8_SB(0, 1), b2 + hstep, voffB); PG8_STAGE(PG8_SA(0, 0), a2, voffA);
;             PG8_WAIT_V(8); PG8_WAIT_L(0); PG8_BAR; PG8_MMA(1, 0, At, B0); PG8_MMA(1, 1, At, B1); PG8_BAR; PG8_SCHED;
.LBB0_196:
	s_ashr_i32 s91, s90, 31
	s_lshl_b64 s[54:55], s[90:91], 19
	s_add_u32 s94, s7, s54
	s_addc_u32 s95, s16, s55
	s_and_b64 s[54:55], s[48:49], exec
	s_cselect_b32 s68, s95, s13
	s_cselect_b32 s69, s94, s12
	s_ashr_i32 s79, s78, 31
	s_lshl_b64 s[54:55], s[78:79], 19
	s_add_u32 s60, s39, s54
	s_addc_u32 s61, s87, s55
	s_and_b64 s[54:55], s[48:49], exec
	s_cselect_b32 s73, s61, s51
	s_cselect_b32 s77, s60, s50
	s_add_u32 s12, s12, 0x40080
	s_addc_u32 s13, s13, 0
	s_add_u32 s79, s50, 0x100
	s_addc_u32 s80, s51, 0
	s_mov_b32 s81, -2
	s_add_u32 s50, s12, 0xfffc0080
	s_addc_u32 s51, s13, -1
	s_add_i32 s83, 0, 0x10000
	s_cmp_eq_u32 s81, 12
	s_cselect_b32 s55, s68, s51
	s_cselect_b32 s54, s69, s50
	s_cselect_b32 s51, s73, s80
	s_cselect_b32 s50, s77, s79
	s_add_i32 s91, 0, 0x14000
	v_add_u32_e32 v154, s83, v170
	v_add_u32_e32 v158, s91, v170
	ds_read_b128 v[142:145], v154
	ds_read_b128 v[146:149], v154 offset:1024
	ds_read_b128 v[150:153], v154 offset:2048
	ds_read_b128 v[154:157], v154 offset:3072
	ds_read_b128 v[202:205], v158
	ds_read_b128 v[206:209], v158 offset:1024
	ds_read_b128 v[210:213], v158 offset:2048
	ds_read_b128 v[214:217], v158 offset:3072
	v_lshl_add_u64 v[158:159], s[12:13], 0, v[138:139]
	s_add_i32 m0, s21, 0xc000
	ds_read_b128 v[218:221], v190
	ds_read_b128 v[222:225], v190 offset:1024
	ds_read_b128 v[226:229], v190 offset:2048
	ds_read_b128 v[230:233], v190 offset:3072
	ds_read_b128 v[234:237], v190 offset:4096
	ds_read_b128 v[238:241], v190 offset:5120
	ds_read_b128 v[242:245], v190 offset:6144
	ds_read_b128 v[246:249], v190 offset:7168
	global_load_lds_dwordx4 v[158:159], off
	v_lshl_add_u64 v[158:159], s[12:13], 0, v[140:141]
	s_add_i32 m0, s21, 0xe000
	s_nop 0
	global_load_lds_dwordx4 v[158:159], off
	s_waitcnt vmcnt(8)
	s_waitcnt lgkmcnt(0)
	s_barrier
	s_setprio 1
	s_waitcnt lgkmcnt(0)
	v_mfma_f32_16x16x32_bf16 v[42:45], v[142:145], v[218:221], 0
	v_mfma_f32_16x16x32_bf16 v[46:49], v[150:153], v[218:221], 0
	v_mfma_f32_16x16x32_bf16 v[66:69], v[142:145], v[226:229], 0
	v_mfma_f32_16x16x32_bf16 v[70:73], v[150:153], v[226:229], 0
	v_mfma_f32_16x16x32_bf16 v[98:101], v[142:145], v[234:237], 0
	v_mfma_f32_16x16x32_bf16 v[102:105], v[150:153], v[234:237], 0
	v_mfma_f32_16x16x32_bf16 v[122:125], v[142:145], v[242:245], 0
	v_mfma_f32_16x16x32_bf16 v[126:129], v[150:153], v[242:245], 0
	v_mfma_f32_16x16x32_bf16 v[42:45], v[146:149], v[222:225], v[42:45]
	v_mfma_f32_16x16x32_bf16 v[46:49], v[154:157], v[222:225], v[46:49]
	v_mfma_f32_16x16x32_bf16 v[66:69], v[146:149], v[230:233], v[66:69]
	v_mfma_f32_16x16x32_bf16 v[70:73], v[154:157], v[230:233], v[70:73]
	v_mfma_f32_16x16x32_bf16 v[98:101], v[146:149], v[238:241], v[98:101]
	v_mfma_f32_16x16x32_bf16 v[102:105], v[154:157], v[238:241], v[102:105]
	v_mfma_f32_16x16x32_bf16 v[122:125], v[146:149], v[246:249], v[122:125]
	v_mfma_f32_16x16x32_bf16 v[126:129], v[154:157], v[246:249], v[126:129]
	s_setprio 0
	s_setprio 1
	v_mfma_f32_16x16x32_bf16 v[62:65], v[202:205], v[218:221], 0
	v_mfma_f32_16x16x32_bf16 v[58:61], v[210:213], v[218:221], 0
	v_mfma_f32_16x16x32_bf16 v[86:89], v[202:205], v[226:229], 0
	v_mfma_f32_16x16x32_bf16 v[82:85], v[210:213], v[226:229], 0
	v_mfma_f32_16x16x32_bf16 v[110:113], v[202:205], v[234:237], 0
	v_mfma_f32_16x16x32_bf16 v[106:109], v[210:213], v[234:237], 0
	v_mfma_f32_16x16x32_bf16 v[118:121], v[202:205], v[242:245], 0
	v_mfma_f32_16x16x32_bf16 v[114:117], v[210:213], v[242:245], 0
	v_mfma_f32_16x16x32_bf16 v[62:65], v[206:209], v[222:225], v[62:65]
	v_mfma_f32_16x16x32_bf16 v[58:61], v[214:217], v[222:225], v[58:61]
	v_mfma_f32_16x16x32_bf16 v[86:89], v[206:209], v[230:233], v[86:89]
	v_mfma_f32_16x16x32_bf16 v[82:85], v[214:217], v[230:233], v[82:85]
	v_mfma_f32_16x16x32_bf16 v[110:113], v[206:209], v[238:241], v[110:113]
	v_mfma_f32_16x16x32_bf16 v[106:109], v[214:217], v[238:241], v[106:109]
	v_mfma_f32_16x16x32_bf16 v[118:121], v[206:209], v[246:249], v[118:121]
	v_mfma_f32_16x16x32_bf16 v[114:117], v[214:217], v[246:249], v[114:117]
	s_setprio 0
	s_barrier
	s_add_i32 s83, s83, s33
	v_lshl_add_u64 v[158:159], s[50:51], 0, v[0:1]
	s_mov_b32 m0, s83
	ds_read_b128 v[218:221], v190 offset:16384
	ds_read_b128 v[222:225], v190 offset:17408
	ds_read_b128 v[226:229], v190 offset:18432
	ds_read_b128 v[230:233], v190 offset:19456
	ds_read_b128 v[234:237], v190 offset:20480
	ds_read_b128 v[238:241], v190 offset:21504
	ds_read_b128 v[242:245], v190 offset:22528
	ds_read_b128 v[246:249], v190 offset:23552
	global_load_lds_dwordx4 v[158:159], off
	s_add_i32 m0, s83, 0x2000
	s_add_u32 s84, s50, 0x40000
	v_lshl_add_u64 v[160:161], s[50:51], 0, v[134:135]
	s_addc_u32 s85, s51, 0
	s_add_i32 s83, s91, s33
	global_load_lds_dwordx4 v[160:161], off
	v_lshl_add_u64 v[162:163], s[84:85], 0, v[0:1]
	s_mov_b32 m0, s83
	v_lshl_add_u64 v[164:165], s[54:55], 0, v[132:133]
	global_load_lds_dwordx4 v[162:163], off
	v_lshl_add_u64 v[162:163], s[84:85], 0, v[134:135]
	s_add_i32 m0, s83, 0x2000
	s_nop 0
	global_load_lds_dwordx4 v[162:163], off
	v_lshl_add_u64 v[162:163], s[54:55], 0, v[130:131]
	s_mov_b32 m0, s21
	s_nop 0
	global_load_lds_dwordx4 v[162:163], off
	s_mov_b32 m0, s19
	s_nop 0
	global_load_lds_dwordx4 v[164:165], off
	s_waitcnt vmcnt(8)
	s_waitcnt lgkmcnt(0)
	s_barrier
; #define PG8_STAGE(bufoff, gbase, voff) do { _Pragma("unroll") for (int _i = 0; _i < 2; ++_i) \
;         __builtin_amdgcn_global_load_lds((const unsigned*)((const char*)(gbase) + (voff)[_i]), (LAS unsigned*)(lds + (bufoff) + ldsw + _i * 8192), 16, 0, 0); } while (0)
; #define PG8_LDA(dst, b, h) do { _Pragma("unroll") for (int m = 0; m < 4; ++m) _Pragma("unroll") for (int k = 0; k < 2; ++k) dst[m][k] = *(const LAS bf16x8*)(lds + PG8_SA(b, h) + aoff + m * 2048 + k * 1024); } while (0)
; #define PG8_LDB(dst, b, h) do { _Pragma("unroll") for (int n = 0; n < 2; ++n) _Pragma("unroll") for (int k = 0; k < 2; ++k) dst[n][k] = *(const LAS bf16x8*)(lds + PG8_SB(b, h) + boff + n * 2048 + k * 1024); } while (0)
; #define PG8_MMA(ai, bj, At, Bt) do { __builtin_amdgcn_s_setprio(1); _Pragma("unroll") for (int m = 0; m < 4; ++m) _Pragma("unroll") for (int n = 0; n < 2; ++n) _Pragma("unroll") for (int k = 0; k < 2; ++k) \
;         acc[ai][bj][m][n] = __builtin_amdgcn_mfma_f32_16x16x32_bf16(Bt[n][k], At[m][k], acc[ai][bj][m][n], 0, 0, 0); __builtin_amdgcn_s_setprio(0); } while (0)
; #define PG8_WAIT_V(n) asm volatile("s_waitcnt vmcnt(" #n ")" ::: "memory")
; #define PG8_WAIT_L(n) asm volatile("s_waitcnt lgkmcnt(" #n ")" ::: "memory")
; #define PG8_BAR __builtin_amdgcn_s_barrier()
; #define PG8_SCHED __builtin_amdgcn_sched_barrier(0)
; template <class Epi, class Sched, bool ALIGN_EPI = true>
; __device__ __forceinline__ void gemm_phase(LAS unsigned char* lds, const int wave_s, const int K, const Sched& S, const Epi& E) {
;     ...
;             PG8_WAIT_V(8); PG8_WAIT_L(0); PG8_BAR; PG8_MMA(1, 0, At, B0); PG8_MMA(1, 1, At, B1); PG8_BAR; PG8_SCHED;
;             PG8_LDB(B0, 1, 0); PG8_LDB(B1, 1, 1); PG8_SCHED; PG8_LDA(At, 1, 0); PG8_STAGE(PG8_SA(0, 1), a2 + hstep, voffA);
;             PG8_WAIT_V(8); PG8_WAIT_L(0); PG8_BAR; PG8_MMA(0, 0, At, B0); PG8_MMA(0, 1, At, B1); PG8_BAR; PG8_SCHED;
;             PG8_LDA(At, 1, 1); PG8_STAGE(PG8_SB(1, 0), b3, voffB); PG8_STAGE(PG8_SB(1, 1), b3 + hstep, voffB); PG8_STAGE(PG8_SA(1, 0), a3, voffA);
	s_setprio 1
	s_waitcnt lgkmcnt(0)
	v_mfma_f32_16x16x32_bf16 v[94:97], v[142:145], v[218:221], 0
	v_mfma_f32_16x16x32_bf16 v[90:93], v[150:153], v[218:221], 0
	v_mfma_f32_16x16x32_bf16 v[54:57], v[142:145], v[226:229], 0
	v_mfma_f32_16x16x32_bf16 v[50:53], v[150:153], v[226:229], 0
	v_mfma_f32_16x16x32_bf16 v[30:33], v[142:145], v[234:237], 0
	v_mfma_f32_16x16x32_bf16 v[26:29], v[150:153], v[234:237], 0
	v_mfma_f32_16x16x32_bf16 v[14:17], v[142:145], v[242:245], 0
	v_mfma_f32_16x16x32_bf16 v[10:13], v[150:153], v[242:245], 0
	v_mfma_f32_16x16x32_bf16 v[94:97], v[146:149], v[222:225], v[94:97]
	v_mfma_f32_16x16x32_bf16 v[90:93], v[154:157], v[222:225], v[90:93]
	v_mfma_f32_16x16x32_bf16 v[54:57], v[146:149], v[230:233], v[54:57]
	v_mfma_f32_16x16x32_bf16 v[50:53], v[154:157], v[230:233], v[50:53]
	v_mfma_f32_16x16x32_bf16 v[30:33], v[146:149], v[238:241], v[30:33]
	v_mfma_f32_16x16x32_bf16 v[26:29], v[154:157], v[238:241], v[26:29]
	v_mfma_f32_16x16x32_bf16 v[14:17], v[146:149], v[246:249], v[14:17]
	v_mfma_f32_16x16x32_bf16 v[10:13], v[154:157], v[246:249], v[10:13]
	s_setprio 0
	s_setprio 1
	v_mfma_f32_16x16x32_bf16 v[78:81], v[202:205], v[218:221], 0
	v_mfma_f32_16x16x32_bf16 v[74:77], v[210:213], v[218:221], 0
	v_mfma_f32_16x16x32_bf16 v[38:41], v[202:205], v[226:229], 0
	v_mfma_f32_16x16x32_bf16 v[34:37], v[210:213], v[226:229], 0
	v_mfma_f32_16x16x32_bf16 v[22:25], v[202:205], v[234:237], 0
	v_mfma_f32_16x16x32_bf16 v[18:21], v[210:213], v[234:237], 0
	v_mfma_f32_16x16x32_bf16 v[6:9], v[202:205], v[242:245], 0
	v_mfma_f32_16x16x32_bf16 v[2:5], v[210:213], v[242:245], 0
	v_mfma_f32_16x16x32_bf16 v[78:81], v[206:209], v[222:225], v[78:81]
	v_mfma_f32_16x16x32_bf16 v[74:77], v[214:217], v[222:225], v[74:77]
	v_mfma_f32_16x16x32_bf16 v[38:41], v[206:209], v[230:233], v[38:41]
	v_mfma_f32_16x16x32_bf16 v[34:37], v[214:217], v[230:233], v[34:37]
	v_mfma_f32_16x16x32_bf16 v[22:25], v[206:209], v[238:241], v[22:25]
	v_mfma_f32_16x16x32_bf16 v[18:21], v[214:217], v[238:241], v[18:21]
	v_mfma_f32_16x16x32_bf16 v[6:9], v[206:209], v[246:249], v[6:9]
	v_mfma_f32_16x16x32_bf16 v[2:5], v[214:217], v[246:249], v[2:5]
	s_setprio 0
	s_barrier
	s_add_i32 s83, 0, 0x18000
	s_add_i32 s84, 0, 0x1c000
	v_add_u32_e32 v154, s83, v170
	v_add_u32_e32 v166, s84, v170
	ds_read_b128 v[142:145], v154
	ds_read_b128 v[146:149], v154 offset:1024
	ds_read_b128 v[150:153], v154 offset:2048
	ds_read_b128 v[154:157], v154 offset:3072
	ds_read_b128 v[202:205], v166
	ds_read_b128 v[206:209], v166 offset:1024
	ds_read_b128 v[210:213], v166 offset:2048
	ds_read_b128 v[214:217], v166 offset:3072
	s_add_u32 s54, s54, 0x40000
	s_addc_u32 s55, s55, 0
	s_mov_b32 m0, s28
	v_lshl_add_u64 v[166:167], s[54:55], 0, v[130:131]
	ds_read_b128 v[218:221], v190 offset:32768
	ds_read_b128 v[222:225], v190 offset:33792
	ds_read_b128 v[226:229], v190 offset:34816
	ds_read_b128 v[230:233], v190 offset:35840
	ds_read_b128 v[234:237], v190 offset:36864
	ds_read_b128 v[238:241], v190 offset:37888
	ds_read_b128 v[242:245], v190 offset:38912
	ds_read_b128 v[246:249], v190 offset:39936
	global_load_lds_dwordx4 v[166:167], off
	v_lshl_add_u64 v[166:167], s[54:55], 0, v[132:133]
	s_mov_b32 m0, s30
	s_nop 0
	global_load_lds_dwordx4 v[166:167], off
	s_waitcnt vmcnt(8)
	s_waitcnt lgkmcnt(0)
	s_barrier
	s_setprio 1
	s_waitcnt lgkmcnt(0)
	v_mfma_f32_16x16x32_bf16 v[42:45], v[142:145], v[218:221], v[42:45]
	v_mfma_f32_16x16x32_bf16 v[46:49], v[150:153], v[218:221], v[46:49]
	v_mfma_f32_16x16x32_bf16 v[66:69], v[142:145], v[226:229], v[66:69]
	v_mfma_f32_16x16x32_bf16 v[70:73], v[150:153], v[226:229], v[70:73]
	v_mfma_f32_16x16x32_bf16 v[98:101], v[142:145], v[234:237], v[98:101]
	v_mfma_f32_16x16x32_bf16 v[102:105], v[150:153], v[234:237], v[102:105]
	v_mfma_f32_16x16x32_bf16 v[122:125], v[142:145], v[242:245], v[122:125]
	v_mfma_f32_16x16x32_bf16 v[126:129], v[150:153], v[242:245], v[126:129]
	v_mfma_f32_16x16x32_bf16 v[42:45], v[146:149], v[222:225], v[42:45]
	v_mfma_f32_16x16x32_bf16 v[46:49], v[154:157], v[222:225], v[46:49]
	v_mfma_f32_16x16x32_bf16 v[66:69], v[146:149], v[230:233], v[66:69]
	v_mfma_f32_16x16x32_bf16 v[70:73], v[154:157], v[230:233], v[70:73]
	v_mfma_f32_16x16x32_bf16 v[98:101], v[146:149], v[238:241], v[98:101]
	v_mfma_f32_16x16x32_bf16 v[102:105], v[154:157], v[238:241], v[102:105]
	v_mfma_f32_16x16x32_bf16 v[122:125], v[146:149], v[246:249], v[122:125]
	v_mfma_f32_16x16x32_bf16 v[126:129], v[154:157], v[246:249], v[126:129]
	s_setprio 0
	s_setprio 1
	v_mfma_f32_16x16x32_bf16 v[62:65], v[202:205], v[218:221], v[62:65]
	v_mfma_f32_16x16x32_bf16 v[58:61], v[210:213], v[218:221], v[58:61]
	v_mfma_f32_16x16x32_bf16 v[86:89], v[202:205], v[226:229], v[86:89]
	v_mfma_f32_16x16x32_bf16 v[82:85], v[210:213], v[226:229], v[82:85]
	v_mfma_f32_16x16x32_bf16 v[110:113], v[202:205], v[234:237], v[110:113]
	v_mfma_f32_16x16x32_bf16 v[106:109], v[210:213], v[234:237], v[106:109]
	v_mfma_f32_16x16x32_bf16 v[118:121], v[202:205], v[242:245], v[118:121]
	v_mfma_f32_16x16x32_bf16 v[114:117], v[210:213], v[242:245], v[114:117]
	v_mfma_f32_16x16x32_bf16 v[62:65], v[206:209], v[222:225], v[62:65]
	v_mfma_f32_16x16x32_bf16 v[58:61], v[214:217], v[222:225], v[58:61]
	v_mfma_f32_16x16x32_bf16 v[86:89], v[206:209], v[230:233], v[86:89]
	v_mfma_f32_16x16x32_bf16 v[82:85], v[214:217], v[230:233], v[82:85]
	v_mfma_f32_16x16x32_bf16 v[110:113], v[206:209], v[238:241], v[110:113]
	v_mfma_f32_16x16x32_bf16 v[106:109], v[214:217], v[238:241], v[106:109]
	v_mfma_f32_16x16x32_bf16 v[118:121], v[206:209], v[246:249], v[118:121]
	v_mfma_f32_16x16x32_bf16 v[114:117], v[214:217], v[246:249], v[114:117]
	s_setprio 0
	s_barrier
; #define PG8_STAGE(bufoff, gbase, voff) do { _Pragma("unroll") for (int _i = 0; _i < 2; ++_i) \
;         __builtin_amdgcn_global_load_lds((const unsigned*)((const char*)(gbase) + (voff)[_i]), (LAS unsigned*)(lds + (bufoff) + ldsw + _i * 8192), 16, 0, 0); } while (0)
; #define PG8_LDA(dst, b, h) do { _Pragma("unroll") for (int m = 0; m < 4; ++m) _Pragma("unroll") for (int k = 0; k < 2; ++k) dst[m][k] = *(const LAS bf16x8*)(lds + PG8_SA(b, h) + aoff + m * 2048 + k * 1024); } while (0)
; #define PG8_MMA(ai, bj, At, Bt) do { __builtin_amdgcn_s_setprio(1); _Pragma("unroll") for (int m = 0; m < 4; ++m) _Pragma("unroll") for (int n = 0; n < 2; ++n) _Pragma("unroll") for (int k = 0; k < 2; ++k) \
;         acc[ai][bj][m][n] = __builtin_amdgcn_mfma_f32_16x16x32_bf16(Bt[n][k], At[m][k], acc[ai][bj][m][n], 0, 0, 0); __builtin_amdgcn_s_setprio(0); } while (0)
; #define PG8_WAIT_V(n) asm volatile("s_waitcnt vmcnt(" #n ")" ::: "memory")
; #define PG8_WAIT_L(n) asm volatile("s_waitcnt lgkmcnt(" #n ")" ::: "memory")
; #define PG8_BAR __builtin_amdgcn_s_barrier()
; #define PG8_SCHED __builtin_amdgcn_sched_barrier(0)
; template <class Epi, class Sched, bool ALIGN_EPI = true>
; __device__ __forceinline__ void gemm_phase(LAS unsigned char* lds, const int wave_s, const int K, const Sched& S, const Epi& E) {
;     ...
;             PG8_LDA(At, 1, 1); PG8_STAGE(PG8_SB(1, 0), b3, voffB); PG8_STAGE(PG8_SB(1, 1), b3 + hstep, voffB); PG8_STAGE(PG8_SA(1, 0), a3, voffA);
;             PG8_WAIT_V(8); PG8_WAIT_L(0); PG8_BAR; PG8_MMA(1, 0, At, B0); PG8_MMA(1, 1, At, B1); PG8_BAR; PG8_SCHED;
;         }
	s_add_i32 s54, s83, s33
	v_lshl_add_u64 v[158:159], v[158:159], 0, s[22:23]
	s_mov_b32 m0, s54
	ds_read_b128 v[218:221], v190 offset:49152
	ds_read_b128 v[222:225], v190 offset:50176
	ds_read_b128 v[226:229], v190 offset:51200
	ds_read_b128 v[230:233], v190 offset:52224
	ds_read_b128 v[234:237], v190 offset:53248
	ds_read_b128 v[238:241], v190 offset:54272
	ds_read_b128 v[242:245], v190 offset:55296
	ds_read_b128 v[246:249], v190 offset:56320
	global_load_lds_dwordx4 v[158:159], off
	s_add_i32 m0, s54, 0x2000
	s_add_u32 s50, s50, 0x40080
	v_lshl_add_u64 v[158:159], v[160:161], 0, s[22:23]
	s_addc_u32 s51, s51, 0
	s_add_i32 s54, s84, s33
	global_load_lds_dwordx4 v[158:159], off
	v_lshl_add_u64 v[158:159], s[50:51], 0, v[0:1]
	s_mov_b32 m0, s54
	s_nop 0
	global_load_lds_dwordx4 v[158:159], off
	v_lshl_add_u64 v[158:159], s[50:51], 0, v[134:135]
	s_add_i32 m0, s54, 0x2000
	s_nop 0
	global_load_lds_dwordx4 v[158:159], off
	v_lshl_add_u64 v[158:159], v[162:163], 0, s[22:23]
	s_mov_b32 m0, s56
	s_nop 0
	global_load_lds_dwordx4 v[158:159], off
	v_lshl_add_u64 v[158:159], v[164:165], 0, s[22:23]
	s_mov_b32 m0, s57
	s_nop 0
	global_load_lds_dwordx4 v[158:159], off
	s_waitcnt vmcnt(8)
	s_waitcnt lgkmcnt(0)
	s_barrier
	s_setprio 1
	s_waitcnt lgkmcnt(0)
	v_mfma_f32_16x16x32_bf16 v[94:97], v[142:145], v[218:221], v[94:97]
	v_mfma_f32_16x16x32_bf16 v[90:93], v[150:153], v[218:221], v[90:93]
	v_mfma_f32_16x16x32_bf16 v[54:57], v[142:145], v[226:229], v[54:57]
	v_mfma_f32_16x16x32_bf16 v[50:53], v[150:153], v[226:229], v[50:53]
	v_mfma_f32_16x16x32_bf16 v[30:33], v[142:145], v[234:237], v[30:33]
	v_mfma_f32_16x16x32_bf16 v[26:29], v[150:153], v[234:237], v[26:29]
	v_mfma_f32_16x16x32_bf16 v[14:17], v[142:145], v[242:245], v[14:17]
	v_mfma_f32_16x16x32_bf16 v[10:13], v[150:153], v[242:245], v[10:13]
	v_mfma_f32_16x16x32_bf16 v[94:97], v[146:149], v[222:225], v[94:97]
	v_mfma_f32_16x16x32_bf16 v[90:93], v[154:157], v[222:225], v[90:93]
	v_mfma_f32_16x16x32_bf16 v[54:57], v[146:149], v[230:233], v[54:57]
	v_mfma_f32_16x16x32_bf16 v[50:53], v[154:157], v[230:233], v[50:53]
	v_mfma_f32_16x16x32_bf16 v[30:33], v[146:149], v[238:241], v[30:33]
	v_mfma_f32_16x16x32_bf16 v[26:29], v[154:157], v[238:241], v[26:29]
	v_mfma_f32_16x16x32_bf16 v[14:17], v[146:149], v[246:249], v[14:17]
	v_mfma_f32_16x16x32_bf16 v[10:13], v[154:157], v[246:249], v[10:13]
	s_setprio 0
	s_setprio 1
	v_mfma_f32_16x16x32_bf16 v[78:81], v[202:205], v[218:221], v[78:81]
	v_mfma_f32_16x16x32_bf16 v[74:77], v[210:213], v[218:221], v[74:77]
	v_mfma_f32_16x16x32_bf16 v[38:41], v[202:205], v[226:229], v[38:41]
	v_mfma_f32_16x16x32_bf16 v[34:37], v[210:213], v[226:229], v[34:37]
	v_mfma_f32_16x16x32_bf16 v[22:25], v[202:205], v[234:237], v[22:25]
	v_mfma_f32_16x16x32_bf16 v[18:21], v[210:213], v[234:237], v[18:21]
	v_mfma_f32_16x16x32_bf16 v[6:9], v[202:205], v[242:245], v[6:9]
	v_mfma_f32_16x16x32_bf16 v[2:5], v[210:213], v[242:245], v[2:5]
	v_mfma_f32_16x16x32_bf16 v[78:81], v[206:209], v[222:225], v[78:81]
	v_mfma_f32_16x16x32_bf16 v[74:77], v[214:217], v[222:225], v[74:77]
	v_mfma_f32_16x16x32_bf16 v[38:41], v[206:209], v[230:233], v[38:41]
	v_mfma_f32_16x16x32_bf16 v[34:37], v[214:217], v[230:233], v[34:37]
	v_mfma_f32_16x16x32_bf16 v[22:25], v[206:209], v[238:241], v[22:25]
	v_mfma_f32_16x16x32_bf16 v[18:21], v[214:217], v[238:241], v[18:21]
	v_mfma_f32_16x16x32_bf16 v[6:9], v[206:209], v[246:249], v[6:9]
	v_mfma_f32_16x16x32_bf16 v[2:5], v[214:217], v[246:249], v[2:5]
	s_setprio 0
	s_barrier
	s_add_i32 s81, s81, 2
	s_add_u32 s12, s12, 0x100
	s_addc_u32 s13, s13, 0
	s_add_u32 s79, s79, 0x100
	s_addc_u32 s80, s80, 0
	s_cmp_gt_u32 s81, 13

; #define PG8_STAGE(bufoff, gbase, voff) do { _Pragma("unroll") for (int _i = 0; _i < 2; ++_i) \
;         __builtin_amdgcn_global_load_lds((const unsigned*)((const char*)(gbase) + (voff)[_i]), (LAS unsigned*)(lds + (bufoff) + ldsw + _i * 8192), 16, 0, 0); } while (0)
; #define PG8_LDA(dst, b, h) do { _Pragma("unroll") for (int m = 0; m < 4; ++m) _Pragma("unroll") for (int k = 0; k < 2; ++k) dst[m][k] = *(const LAS bf16x8*)(lds + PG8_SA(b, h) + aoff + m * 2048 + k * 1024); } while (0)
; #define PG8_LDB(dst, b, h) do { _Pragma("unroll") for (int n = 0; n < 2; ++n) _Pragma("unroll") for (int k = 0; k < 2; ++k) dst[n][k] = *(const LAS bf16x8*)(lds + PG8_SB(b, h) + boff + n * 2048 + k * 1024); } while (0)
; #define PG8_MMA(ai, bj, At, Bt) do { __builtin_amdgcn_s_setprio(1); _Pragma("unroll") for (int m = 0; m < 4; ++m) _Pragma("unroll") for (int n = 0; n < 2; ++n) _Pragma("unroll") for (int k = 0; k < 2; ++k) \
;         acc[ai][bj][m][n] = __builtin_amdgcn_mfma_f32_16x16x32_bf16(Bt[n][k], At[m][k], acc[ai][bj][m][n], 0, 0, 0); __builtin_amdgcn_s_setprio(0); } while (0)
; #define PG8_WAIT_V(n) asm volatile("s_waitcnt vmcnt(" #n ")" ::: "memory")
; #define PG8_WAIT_L(n) asm volatile("s_waitcnt lgkmcnt(" #n ")" ::: "memory")
; #define PG8_BAR __builtin_amdgcn_s_barrier()
; #define PG8_SCHED __builtin_amdgcn_sched_barrier(0)
; template <class Epi, class Sched, bool ALIGN_EPI = true>
; __device__ __forceinline__ void gemm_phase(LAS unsigned char* lds, const int wave_s, const int K, const Sched& S, const Epi& E) {
;     ...
;             PG8_LDB(B0, 0, 0); PG8_LDB(B1, 0, 1); PG8_SCHED; PG8_LDA(At, 0, 0); PG8_STAGE(PG8_SA(1, 1), a1 + hstep, voffA);
;             PG8_WAIT_V(8); PG8_WAIT_L(0); PG8_BAR; PG8_MMA(0, 0, At, B0); PG8_MMA(0, 1, At, B1); PG8_BAR; PG8_SCHED;
;             PG8_LDA(At, 0, 1); PG8_STAGE(PG8_SB(0, 0), b2, voffB); PG8_STAGE(PG8_SB(0, 1), b2 + hstep, voffB); PG8_STAGE(PG8_SA(0, 0), a2, voffA);
;             PG8_WAIT_V(8); PG8_WAIT_L(0); PG8_BAR; PG8_MMA(1, 0, At, B0); PG8_MMA(1, 1, At, B1); PG8_BAR; PG8_SCHED;
;     ...
; #pragma unroll
;         for (int a = 0; a < 2; ++a)
; #pragma unroll
;             for (int b = 0; b < 2; ++b)
; #pragma unroll
;                 for (int m = 0; m < 4; ++m)
; #pragma unroll
;                     for (int n = 0; n < 2; ++n) acc[a][b][m][n] = (f32x4){0.f, 0.f, 0.f, 0.f};
;         cur = nxt; cA = nA; cB = nB; ++ui;
.LBB0_298:
	s_add_u32 s12, s12, 0x40080
	s_addc_u32 s13, s13, 0
	s_add_u32 s18, s44, 0x100
	s_addc_u32 s19, s45, 0
	s_mov_b32 s30, -2
	s_add_u32 s36, s12, 0xfffc0080
	s_addc_u32 s44, s13, -1
	s_add_i32 s51, 0, 0x10000
	s_cmp_eq_u32 s30, 12
	s_cselect_b32 s47, s55, s44
	s_cselect_b32 s46, s54, s36
	s_cselect_b32 s45, s63, s19
	s_cselect_b32 s44, s62, s18
	s_add_i32 s36, 0, 0x14000
	v_add_u32_e32 v156, s51, v171
	v_add_u32_e32 v160, s36, v171
	ds_read_b128 v[130:133], v156
	ds_read_b128 v[134:137], v156 offset:1024
	ds_read_b128 v[152:155], v156 offset:2048
	ds_read_b128 v[156:159], v156 offset:3072
	ds_read_b128 v[166:169], v160
	ds_read_b128 v[174:177], v160 offset:1024
	ds_read_b128 v[178:181], v160 offset:2048
	ds_read_b128 v[182:185], v160 offset:3072
	v_lshl_add_u64 v[160:161], s[12:13], 0, v[148:149]
	s_add_i32 m0, s7, 0xc000
	ds_read_b128 v[186:189], v173
	ds_read_b128 v[202:205], v173 offset:1024
	ds_read_b128 v[206:209], v173 offset:2048
	ds_read_b128 v[210:213], v173 offset:3072
	ds_read_b128 v[214:217], v173 offset:4096
	ds_read_b128 v[218:221], v173 offset:5120
	ds_read_b128 v[222:225], v173 offset:6144
	ds_read_b128 v[226:229], v173 offset:7168
	global_load_lds_dwordx4 v[160:161], off
	v_lshl_add_u64 v[160:161], s[12:13], 0, v[150:151]
	s_add_i32 m0, s7, 0xe000
	s_nop 0
	global_load_lds_dwordx4 v[160:161], off
	s_waitcnt vmcnt(8)
	s_waitcnt lgkmcnt(0)
	s_barrier
	s_setprio 1
	s_waitcnt lgkmcnt(0)
	v_mfma_f32_16x16x32_bf16 v[126:129], v[130:133], v[186:189], 0
	v_mfma_f32_16x16x32_bf16 v[122:125], v[152:155], v[186:189], 0
	v_mfma_f32_16x16x32_bf16 v[118:121], v[130:133], v[206:209], 0
	v_mfma_f32_16x16x32_bf16 v[114:117], v[152:155], v[206:209], 0
	v_mfma_f32_16x16x32_bf16 v[110:113], v[130:133], v[214:217], 0
	v_mfma_f32_16x16x32_bf16 v[106:109], v[152:155], v[214:217], 0
	v_mfma_f32_16x16x32_bf16 v[102:105], v[130:133], v[222:225], 0
	v_mfma_f32_16x16x32_bf16 v[98:101], v[152:155], v[222:225], 0
	v_mfma_f32_16x16x32_bf16 v[126:129], v[134:137], v[202:205], v[126:129]
	v_mfma_f32_16x16x32_bf16 v[122:125], v[156:159], v[202:205], v[122:125]
	v_mfma_f32_16x16x32_bf16 v[118:121], v[134:137], v[210:213], v[118:121]
	v_mfma_f32_16x16x32_bf16 v[114:117], v[156:159], v[210:213], v[114:117]
	v_mfma_f32_16x16x32_bf16 v[110:113], v[134:137], v[218:221], v[110:113]
	v_mfma_f32_16x16x32_bf16 v[106:109], v[156:159], v[218:221], v[106:109]
	v_mfma_f32_16x16x32_bf16 v[102:105], v[134:137], v[226:229], v[102:105]
	v_mfma_f32_16x16x32_bf16 v[98:101], v[156:159], v[226:229], v[98:101]
	s_setprio 0
	s_setprio 1
	v_mfma_f32_16x16x32_bf16 v[62:65], v[166:169], v[186:189], 0
	v_mfma_f32_16x16x32_bf16 v[58:61], v[178:181], v[186:189], 0
	v_mfma_f32_16x16x32_bf16 v[54:57], v[166:169], v[206:209], 0
	v_mfma_f32_16x16x32_bf16 v[50:53], v[178:181], v[206:209], 0
	v_mfma_f32_16x16x32_bf16 v[46:49], v[166:169], v[214:217], 0
	v_mfma_f32_16x16x32_bf16 v[42:45], v[178:181], v[214:217], 0
	v_mfma_f32_16x16x32_bf16 v[38:41], v[166:169], v[222:225], 0
	v_mfma_f32_16x16x32_bf16 v[34:37], v[178:181], v[222:225], 0
	v_mfma_f32_16x16x32_bf16 v[62:65], v[174:177], v[202:205], v[62:65]
	v_mfma_f32_16x16x32_bf16 v[58:61], v[182:185], v[202:205], v[58:61]
	v_mfma_f32_16x16x32_bf16 v[54:57], v[174:177], v[210:213], v[54:57]
	v_mfma_f32_16x16x32_bf16 v[50:53], v[182:185], v[210:213], v[50:53]
	v_mfma_f32_16x16x32_bf16 v[46:49], v[174:177], v[218:221], v[46:49]
	v_mfma_f32_16x16x32_bf16 v[42:45], v[182:185], v[218:221], v[42:45]
	v_mfma_f32_16x16x32_bf16 v[38:41], v[174:177], v[226:229], v[38:41]
	v_mfma_f32_16x16x32_bf16 v[34:37], v[182:185], v[226:229], v[34:37]
	s_setprio 0
	s_barrier
	s_add_i32 s51, s51, s33
	v_lshl_add_u64 v[160:161], s[44:45], 0, v[0:1]
	s_mov_b32 m0, s51
	ds_read_b128 v[186:189], v173 offset:16384
	ds_read_b128 v[202:205], v173 offset:17408
	ds_read_b128 v[206:209], v173 offset:18432
	ds_read_b128 v[210:213], v173 offset:19456
	ds_read_b128 v[214:217], v173 offset:20480
	ds_read_b128 v[218:221], v173 offset:21504
	ds_read_b128 v[222:225], v173 offset:22528
	ds_read_b128 v[226:229], v173 offset:23552
	global_load_lds_dwordx4 v[160:161], off
	s_add_i32 m0, s51, 0x2000
	s_add_u32 s56, s44, 0x40000
	v_lshl_add_u64 v[162:163], s[44:45], 0, v[138:139]
	s_addc_u32 s57, s45, 0
	s_add_i32 s36, s36, s33
	global_load_lds_dwordx4 v[162:163], off
	v_lshl_add_u64 v[164:165], s[56:57], 0, v[0:1]
	s_mov_b32 m0, s36
	v_lshl_add_u64 v[190:191], s[46:47], 0, v[140:141]
	global_load_lds_dwordx4 v[164:165], off
	v_lshl_add_u64 v[164:165], s[56:57], 0, v[138:139]
	s_add_i32 m0, s36, 0x2000
	s_nop 0
	global_load_lds_dwordx4 v[164:165], off
	v_lshl_add_u64 v[164:165], s[46:47], 0, v[142:143]
	s_mov_b32 m0, s7
	s_nop 0
	global_load_lds_dwordx4 v[164:165], off
	s_mov_b32 m0, s16
	s_nop 0
	global_load_lds_dwordx4 v[190:191], off
	s_waitcnt vmcnt(8)
	s_waitcnt lgkmcnt(0)
	s_barrier
; #define PG8_STAGE(bufoff, gbase, voff) do { _Pragma("unroll") for (int _i = 0; _i < 2; ++_i) \
;         __builtin_amdgcn_global_load_lds((const unsigned*)((const char*)(gbase) + (voff)[_i]), (LAS unsigned*)(lds + (bufoff) + ldsw + _i * 8192), 16, 0, 0); } while (0)
; #define PG8_LDA(dst, b, h) do { _Pragma("unroll") for (int m = 0; m < 4; ++m) _Pragma("unroll") for (int k = 0; k < 2; ++k) dst[m][k] = *(const LAS bf16x8*)(lds + PG8_SA(b, h) + aoff + m * 2048 + k * 1024); } while (0)
; #define PG8_LDB(dst, b, h) do { _Pragma("unroll") for (int n = 0; n < 2; ++n) _Pragma("unroll") for (int k = 0; k < 2; ++k) dst[n][k] = *(const LAS bf16x8*)(lds + PG8_SB(b, h) + boff + n * 2048 + k * 1024); } while (0)
; #define PG8_MMA(ai, bj, At, Bt) do { __builtin_amdgcn_s_setprio(1); _Pragma("unroll") for (int m = 0; m < 4; ++m) _Pragma("unroll") for (int n = 0; n < 2; ++n) _Pragma("unroll") for (int k = 0; k < 2; ++k) \
;         acc[ai][bj][m][n] = __builtin_amdgcn_mfma_f32_16x16x32_bf16(Bt[n][k], At[m][k], acc[ai][bj][m][n], 0, 0, 0); __builtin_amdgcn_s_setprio(0); } while (0)
; #define PG8_WAIT_V(n) asm volatile("s_waitcnt vmcnt(" #n ")" ::: "memory")
; #define PG8_WAIT_L(n) asm volatile("s_waitcnt lgkmcnt(" #n ")" ::: "memory")
; #define PG8_BAR __builtin_amdgcn_s_barrier()
; #define PG8_SCHED __builtin_amdgcn_sched_barrier(0)
; template <class Epi, class Sched, bool ALIGN_EPI = true>
; __device__ __forceinline__ void gemm_phase(LAS unsigned char* lds, const int wave_s, const int K, const Sched& S, const Epi& E) {
;     ...
;             PG8_WAIT_V(8); PG8_WAIT_L(0); PG8_BAR; PG8_MMA(1, 0, At, B0); PG8_MMA(1, 1, At, B1); PG8_BAR; PG8_SCHED;
;             PG8_LDB(B0, 1, 0); PG8_LDB(B1, 1, 1); PG8_SCHED; PG8_LDA(At, 1, 0); PG8_STAGE(PG8_SA(0, 1), a2 + hstep, voffA);
;             PG8_WAIT_V(8); PG8_WAIT_L(0); PG8_BAR; PG8_MMA(0, 0, At, B0); PG8_MMA(0, 1, At, B1); PG8_BAR; PG8_SCHED;
	s_setprio 1
	s_waitcnt lgkmcnt(0)
	v_mfma_f32_16x16x32_bf16 v[94:97], v[130:133], v[186:189], 0
	v_mfma_f32_16x16x32_bf16 v[90:93], v[152:155], v[186:189], 0
	v_mfma_f32_16x16x32_bf16 v[86:89], v[130:133], v[206:209], 0
	v_mfma_f32_16x16x32_bf16 v[82:85], v[152:155], v[206:209], 0
	v_mfma_f32_16x16x32_bf16 v[78:81], v[130:133], v[214:217], 0
	v_mfma_f32_16x16x32_bf16 v[74:77], v[152:155], v[214:217], 0
	v_mfma_f32_16x16x32_bf16 v[70:73], v[130:133], v[222:225], 0
	v_mfma_f32_16x16x32_bf16 v[66:69], v[152:155], v[222:225], 0
	v_mfma_f32_16x16x32_bf16 v[94:97], v[134:137], v[202:205], v[94:97]
	v_mfma_f32_16x16x32_bf16 v[90:93], v[156:159], v[202:205], v[90:93]
	v_mfma_f32_16x16x32_bf16 v[86:89], v[134:137], v[210:213], v[86:89]
	v_mfma_f32_16x16x32_bf16 v[82:85], v[156:159], v[210:213], v[82:85]
	v_mfma_f32_16x16x32_bf16 v[78:81], v[134:137], v[218:221], v[78:81]
	v_mfma_f32_16x16x32_bf16 v[74:77], v[156:159], v[218:221], v[74:77]
	v_mfma_f32_16x16x32_bf16 v[70:73], v[134:137], v[226:229], v[70:73]
	v_mfma_f32_16x16x32_bf16 v[66:69], v[156:159], v[226:229], v[66:69]
	s_setprio 0
	s_setprio 1
	v_mfma_f32_16x16x32_bf16 v[30:33], v[166:169], v[186:189], 0
	v_mfma_f32_16x16x32_bf16 v[26:29], v[178:181], v[186:189], 0
	v_mfma_f32_16x16x32_bf16 v[22:25], v[166:169], v[206:209], 0
	v_mfma_f32_16x16x32_bf16 v[18:21], v[178:181], v[206:209], 0
	v_mfma_f32_16x16x32_bf16 v[14:17], v[166:169], v[214:217], 0
	v_mfma_f32_16x16x32_bf16 v[10:13], v[178:181], v[214:217], 0
	v_mfma_f32_16x16x32_bf16 v[6:9], v[166:169], v[222:225], 0
	v_mfma_f32_16x16x32_bf16 v[2:5], v[178:181], v[222:225], 0
	v_mfma_f32_16x16x32_bf16 v[30:33], v[174:177], v[202:205], v[30:33]
	v_mfma_f32_16x16x32_bf16 v[26:29], v[182:185], v[202:205], v[26:29]
	v_mfma_f32_16x16x32_bf16 v[22:25], v[174:177], v[210:213], v[22:25]
	v_mfma_f32_16x16x32_bf16 v[18:21], v[182:185], v[210:213], v[18:21]
	v_mfma_f32_16x16x32_bf16 v[14:17], v[174:177], v[218:221], v[14:17]
	v_mfma_f32_16x16x32_bf16 v[10:13], v[182:185], v[218:221], v[10:13]
	v_mfma_f32_16x16x32_bf16 v[6:9], v[174:177], v[226:229], v[6:9]
	v_mfma_f32_16x16x32_bf16 v[2:5], v[182:185], v[226:229], v[2:5]
	s_setprio 0
	s_barrier
	s_add_i32 s36, 0, 0x18000
	s_add_i32 s51, 0, 0x1c000
	v_add_u32_e32 v156, s36, v171
	v_add_u32_e32 v182, s51, v171
	ds_read_b128 v[130:133], v156
	ds_read_b128 v[134:137], v156 offset:1024
	ds_read_b128 v[152:155], v156 offset:2048
	ds_read_b128 v[156:159], v156 offset:3072
	ds_read_b128 v[166:169], v182
	ds_read_b128 v[174:177], v182 offset:1024
	ds_read_b128 v[178:181], v182 offset:2048
	ds_read_b128 v[182:185], v182 offset:3072
	s_add_u32 s46, s46, 0x40000
	s_addc_u32 s47, s47, 0
	s_mov_b32 m0, s39
	v_lshl_add_u64 v[196:197], s[46:47], 0, v[142:143]
	ds_read_b128 v[186:189], v173 offset:32768
	ds_read_b128 v[202:205], v173 offset:33792
	ds_read_b128 v[206:209], v173 offset:34816
	ds_read_b128 v[210:213], v173 offset:35840
	ds_read_b128 v[214:217], v173 offset:36864
	ds_read_b128 v[218:221], v173 offset:37888
	ds_read_b128 v[222:225], v173 offset:38912
	ds_read_b128 v[226:229], v173 offset:39936
	global_load_lds_dwordx4 v[196:197], off
	v_lshl_add_u64 v[196:197], s[46:47], 0, v[140:141]
	s_mov_b32 m0, s64
	s_nop 0
	global_load_lds_dwordx4 v[196:197], off
	s_waitcnt vmcnt(8)
	s_waitcnt lgkmcnt(0)
	s_barrier
	s_setprio 1
	s_waitcnt lgkmcnt(0)
	v_mfma_f32_16x16x32_bf16 v[126:129], v[130:133], v[186:189], v[126:129]
	v_mfma_f32_16x16x32_bf16 v[122:125], v[152:155], v[186:189], v[122:125]
	v_mfma_f32_16x16x32_bf16 v[118:121], v[130:133], v[206:209], v[118:121]
	v_mfma_f32_16x16x32_bf16 v[114:117], v[152:155], v[206:209], v[114:117]
	v_mfma_f32_16x16x32_bf16 v[110:113], v[130:133], v[214:217], v[110:113]
	v_mfma_f32_16x16x32_bf16 v[106:109], v[152:155], v[214:217], v[106:109]
	v_mfma_f32_16x16x32_bf16 v[102:105], v[130:133], v[222:225], v[102:105]
	v_mfma_f32_16x16x32_bf16 v[98:101], v[152:155], v[222:225], v[98:101]
	v_mfma_f32_16x16x32_bf16 v[126:129], v[134:137], v[202:205], v[126:129]
	v_mfma_f32_16x16x32_bf16 v[122:125], v[156:159], v[202:205], v[122:125]
	v_mfma_f32_16x16x32_bf16 v[118:121], v[134:137], v[210:213], v[118:121]
	v_mfma_f32_16x16x32_bf16 v[114:117], v[156:159], v[210:213], v[114:117]
	v_mfma_f32_16x16x32_bf16 v[110:113], v[134:137], v[218:221], v[110:113]
	v_mfma_f32_16x16x32_bf16 v[106:109], v[156:159], v[218:221], v[106:109]
	v_mfma_f32_16x16x32_bf16 v[102:105], v[134:137], v[226:229], v[102:105]
	v_mfma_f32_16x16x32_bf16 v[98:101], v[156:159], v[226:229], v[98:101]
	s_setprio 0
	s_setprio 1
	v_mfma_f32_16x16x32_bf16 v[62:65], v[166:169], v[186:189], v[62:65]
	v_mfma_f32_16x16x32_bf16 v[58:61], v[178:181], v[186:189], v[58:61]
	v_mfma_f32_16x16x32_bf16 v[54:57], v[166:169], v[206:209], v[54:57]
	v_mfma_f32_16x16x32_bf16 v[50:53], v[178:181], v[206:209], v[50:53]
	v_mfma_f32_16x16x32_bf16 v[46:49], v[166:169], v[214:217], v[46:49]
	v_mfma_f32_16x16x32_bf16 v[42:45], v[178:181], v[214:217], v[42:45]
	v_mfma_f32_16x16x32_bf16 v[38:41], v[166:169], v[222:225], v[38:41]
	v_mfma_f32_16x16x32_bf16 v[34:37], v[178:181], v[222:225], v[34:37]
	v_mfma_f32_16x16x32_bf16 v[62:65], v[174:177], v[202:205], v[62:65]
	v_mfma_f32_16x16x32_bf16 v[58:61], v[182:185], v[202:205], v[58:61]
	v_mfma_f32_16x16x32_bf16 v[54:57], v[174:177], v[210:213], v[54:57]
	v_mfma_f32_16x16x32_bf16 v[50:53], v[182:185], v[210:213], v[50:53]
	v_mfma_f32_16x16x32_bf16 v[46:49], v[174:177], v[218:221], v[46:49]
	v_mfma_f32_16x16x32_bf16 v[42:45], v[182:185], v[218:221], v[42:45]
	v_mfma_f32_16x16x32_bf16 v[38:41], v[174:177], v[226:229], v[38:41]
	v_mfma_f32_16x16x32_bf16 v[34:37], v[182:185], v[226:229], v[34:37]
	s_setprio 0
	s_barrier
; #define PG8_STAGE(bufoff, gbase, voff) do { _Pragma("unroll") for (int _i = 0; _i < 2; ++_i) \
;         __builtin_amdgcn_global_load_lds((const unsigned*)((const char*)(gbase) + (voff)[_i]), (LAS unsigned*)(lds + (bufoff) + ldsw + _i * 8192), 16, 0, 0); } while (0)
; #define PG8_LDA(dst, b, h) do { _Pragma("unroll") for (int m = 0; m < 4; ++m) _Pragma("unroll") for (int k = 0; k < 2; ++k) dst[m][k] = *(const LAS bf16x8*)(lds + PG8_SA(b, h) + aoff + m * 2048 + k * 1024); } while (0)
; #define PG8_MMA(ai, bj, At, Bt) do { __builtin_amdgcn_s_setprio(1); _Pragma("unroll") for (int m = 0; m < 4; ++m) _Pragma("unroll") for (int n = 0; n < 2; ++n) _Pragma("unroll") for (int k = 0; k < 2; ++k) \
;         acc[ai][bj][m][n] = __builtin_amdgcn_mfma_f32_16x16x32_bf16(Bt[n][k], At[m][k], acc[ai][bj][m][n], 0, 0, 0); __builtin_amdgcn_s_setprio(0); } while (0)
; #define PG8_WAIT_V(n) asm volatile("s_waitcnt vmcnt(" #n ")" ::: "memory")
; #define PG8_WAIT_L(n) asm volatile("s_waitcnt lgkmcnt(" #n ")" ::: "memory")
; #define PG8_BAR __builtin_amdgcn_s_barrier()
; #define PG8_SCHED __builtin_amdgcn_sched_barrier(0)
; template <class Epi, class Sched, bool ALIGN_EPI = true>
; __device__ __forceinline__ void gemm_phase(LAS unsigned char* lds, const int wave_s, const int K, const Sched& S, const Epi& E) {
;     ...
;             PG8_LDA(At, 1, 1); PG8_STAGE(PG8_SB(1, 0), b3, voffB); PG8_STAGE(PG8_SB(1, 1), b3 + hstep, voffB); PG8_STAGE(PG8_SA(1, 0), a3, voffA);
;             PG8_WAIT_V(8); PG8_WAIT_L(0); PG8_BAR; PG8_MMA(1, 0, At, B0); PG8_MMA(1, 1, At, B1); PG8_BAR; PG8_SCHED;
	s_add_i32 s36, s36, s33
	v_lshl_add_u64 v[160:161], v[160:161], 0, s[22:23]
	s_mov_b32 m0, s36
	ds_read_b128 v[186:189], v173 offset:49152
	ds_read_b128 v[202:205], v173 offset:50176
	ds_read_b128 v[206:209], v173 offset:51200
	ds_read_b128 v[210:213], v173 offset:52224
	ds_read_b128 v[214:217], v173 offset:53248
	ds_read_b128 v[218:221], v173 offset:54272
	ds_read_b128 v[222:225], v173 offset:55296
	ds_read_b128 v[226:229], v173 offset:56320
	global_load_lds_dwordx4 v[160:161], off
	s_add_i32 m0, s36, 0x2000
	s_add_u32 s44, s44, 0x40080
	v_lshl_add_u64 v[160:161], v[162:163], 0, s[22:23]
	s_addc_u32 s45, s45, 0
	s_add_i32 s36, s51, s33
	global_load_lds_dwordx4 v[160:161], off
	v_lshl_add_u64 v[160:161], s[44:45], 0, v[0:1]
	s_mov_b32 m0, s36
	s_nop 0
	global_load_lds_dwordx4 v[160:161], off
	v_lshl_add_u64 v[160:161], s[44:45], 0, v[138:139]
	s_add_i32 m0, s36, 0x2000
	s_nop 0
	global_load_lds_dwordx4 v[160:161], off
	v_lshl_add_u64 v[160:161], v[164:165], 0, s[22:23]
	s_mov_b32 m0, s69
	s_nop 0
	global_load_lds_dwordx4 v[160:161], off
	v_lshl_add_u64 v[160:161], v[190:191], 0, s[22:23]
	s_mov_b32 m0, s70
	s_nop 0
	global_load_lds_dwordx4 v[160:161], off
	s_waitcnt vmcnt(8)
	s_waitcnt lgkmcnt(0)
	s_barrier
	s_setprio 1
	s_waitcnt lgkmcnt(0)
	v_mfma_f32_16x16x32_bf16 v[94:97], v[130:133], v[186:189], v[94:97]
	v_mfma_f32_16x16x32_bf16 v[90:93], v[152:155], v[186:189], v[90:93]
	v_mfma_f32_16x16x32_bf16 v[86:89], v[130:133], v[206:209], v[86:89]
	v_mfma_f32_16x16x32_bf16 v[82:85], v[152:155], v[206:209], v[82:85]
	v_mfma_f32_16x16x32_bf16 v[78:81], v[130:133], v[214:217], v[78:81]
	v_mfma_f32_16x16x32_bf16 v[74:77], v[152:155], v[214:217], v[74:77]
	v_mfma_f32_16x16x32_bf16 v[70:73], v[130:133], v[222:225], v[70:73]
	v_mfma_f32_16x16x32_bf16 v[66:69], v[152:155], v[222:225], v[66:69]
	v_mfma_f32_16x16x32_bf16 v[94:97], v[134:137], v[202:205], v[94:97]
	v_mfma_f32_16x16x32_bf16 v[90:93], v[156:159], v[202:205], v[90:93]
	v_mfma_f32_16x16x32_bf16 v[86:89], v[134:137], v[210:213], v[86:89]
	v_mfma_f32_16x16x32_bf16 v[82:85], v[156:159], v[210:213], v[82:85]
	v_mfma_f32_16x16x32_bf16 v[78:81], v[134:137], v[218:221], v[78:81]
	v_mfma_f32_16x16x32_bf16 v[74:77], v[156:159], v[218:221], v[74:77]
	v_mfma_f32_16x16x32_bf16 v[70:73], v[134:137], v[226:229], v[70:73]
	v_mfma_f32_16x16x32_bf16 v[66:69], v[156:159], v[226:229], v[66:69]
	s_setprio 0
	s_setprio 1
	v_mfma_f32_16x16x32_bf16 v[30:33], v[166:169], v[186:189], v[30:33]
	v_mfma_f32_16x16x32_bf16 v[26:29], v[178:181], v[186:189], v[26:29]
	v_mfma_f32_16x16x32_bf16 v[22:25], v[166:169], v[206:209], v[22:25]
	v_mfma_f32_16x16x32_bf16 v[18:21], v[178:181], v[206:209], v[18:21]
	v_mfma_f32_16x16x32_bf16 v[14:17], v[166:169], v[214:217], v[14:17]
	v_mfma_f32_16x16x32_bf16 v[10:13], v[178:181], v[214:217], v[10:13]
	v_mfma_f32_16x16x32_bf16 v[6:9], v[166:169], v[222:225], v[6:9]
	v_mfma_f32_16x16x32_bf16 v[2:5], v[178:181], v[222:225], v[2:5]
	v_mfma_f32_16x16x32_bf16 v[30:33], v[174:177], v[202:205], v[30:33]
	v_mfma_f32_16x16x32_bf16 v[26:29], v[182:185], v[202:205], v[26:29]
	v_mfma_f32_16x16x32_bf16 v[22:25], v[174:177], v[210:213], v[22:25]
	v_mfma_f32_16x16x32_bf16 v[18:21], v[182:185], v[210:213], v[18:21]
	v_mfma_f32_16x16x32_bf16 v[14:17], v[174:177], v[218:221], v[14:17]
	v_mfma_f32_16x16x32_bf16 v[10:13], v[182:185], v[218:221], v[10:13]
	v_mfma_f32_16x16x32_bf16 v[6:9], v[174:177], v[226:229], v[6:9]
	v_mfma_f32_16x16x32_bf16 v[2:5], v[182:185], v[226:229], v[2:5]
	s_setprio 0
	s_barrier
	s_add_i32 s30, s30, 2
	s_add_u32 s12, s12, 0x100
	s_addc_u32 s13, s13, 0
	s_add_u32 s18, s18, 0x100
	s_addc_u32 s19, s19, 0
	s_cmp_gt_u32 s30, 13

; #define PG8_STAGE(bufoff, gbase, voff) do { _Pragma("unroll") for (int _i = 0; _i < 2; ++_i) \
;         __builtin_amdgcn_global_load_lds((const unsigned*)((const char*)(gbase) + (voff)[_i]), (LAS unsigned*)(lds + (bufoff) + ldsw + _i * 8192), 16, 0, 0); } while (0)
; #define PG8_LDA(dst, b, h) do { _Pragma("unroll") for (int m = 0; m < 4; ++m) _Pragma("unroll") for (int k = 0; k < 2; ++k) dst[m][k] = *(const LAS bf16x8*)(lds + PG8_SA(b, h) + aoff + m * 2048 + k * 1024); } while (0)
; #define PG8_LDB(dst, b, h) do { _Pragma("unroll") for (int n = 0; n < 2; ++n) _Pragma("unroll") for (int k = 0; k < 2; ++k) dst[n][k] = *(const LAS bf16x8*)(lds + PG8_SB(b, h) + boff + n * 2048 + k * 1024); } while (0)
; #define PG8_MMA(ai, bj, At, Bt) do { __builtin_amdgcn_s_setprio(1); _Pragma("unroll") for (int m = 0; m < 4; ++m) _Pragma("unroll") for (int n = 0; n < 2; ++n) _Pragma("unroll") for (int k = 0; k < 2; ++k) \
;         acc[ai][bj][m][n] = __builtin_amdgcn_mfma_f32_16x16x32_bf16(Bt[n][k], At[m][k], acc[ai][bj][m][n], 0, 0, 0); __builtin_amdgcn_s_setprio(0); } while (0)
; #define PG8_WAIT_V(n) asm volatile("s_waitcnt vmcnt(" #n ")" ::: "memory")
; template <class Epi, class Sched, bool ALIGN_EPI = true>
; __device__ __forceinline__ void gemm_phase(LAS unsigned char* lds, const int wave_s, const int K, const Sched& S, const Epi& E) {
;     ...
;         const bool has_next = S.next(ui + 1, nxt);
;         const char* nA = has_next ? S.aptr(nxt) : cA; const char* nB = has_next ? S.bptr(nxt) : cB;
;         for (int t = 0; t < nt; t += 2) {
;             const bool last = (t == nt - 2);
;             const char* a1 = cA + (size_t)(t + 1) * kstep;
;             const char* a2 = last ? nA : cA + (size_t)(t + 2) * kstep; const char* b2 = last ? nB : cB + (size_t)(t + 2) * kstep;
;             const char* a3 = a2 + kstep; const char* b3 = b2 + kstep;
;             PG8_LDB(B0, 0, 0); PG8_LDB(B1, 0, 1); PG8_SCHED; PG8_LDA(At, 0, 0); PG8_STAGE(PG8_SA(1, 1), a1 + hstep, voffA);
;             PG8_WAIT_V(8); PG8_WAIT_L(0); PG8_BAR; PG8_MMA(0, 0, At, B0); PG8_MMA(0, 1, At, B1); PG8_BAR; PG8_SCHED;
;             PG8_LDA(At, 0, 1); PG8_STAGE(PG8_SB(0, 0), b2, voffB); PG8_STAGE(PG8_SB(0, 1), b2 + hstep, voffB); PG8_STAGE(PG8_SA(0, 0), a2, voffA);
;             PG8_WAIT_V(8); PG8_WAIT_L(0); PG8_BAR; PG8_MMA(1, 0, At, B0); PG8_MMA(1, 1, At, B1); PG8_BAR; PG8_SCHED;
.LBB0_424:
	s_lshl_b32 s15, s81, 8
	s_addk_i32 s15, 0x1800
	s_cmp_eq_u32 s80, 0
	s_cselect_b32 s20, s81, s15
	s_cselect_b32 s15, 19, 11
	s_cselect_b32 s19, s5, s9
	s_cselect_b32 s28, s4, s8
	s_cselect_b32 s30, s8, s4
	s_cselect_b32 s36, s9, s5
	s_ashr_i32 s21, s20, 31
	s_lshl_b64 s[20:21], s[20:21], s15
	s_add_u32 s70, s28, s20
	s_addc_u32 s71, s19, s21
	s_and_b64 s[20:21], s[76:77], exec
	s_cselect_b32 s19, s71, s13
	s_cselect_b32 s20, s70, s12
	s_ashr_i32 s15, s14, 31
	s_lshl_b64 s[44:45], s[14:15], 19
	s_add_u32 s90, s30, s44
	s_addc_u32 s91, s36, s45
	s_and_b64 s[44:45], s[76:77], exec
	s_cselect_b32 s15, s91, s35
	s_cselect_b32 s21, s90, s34
	s_add_u32 s12, s12, 0x40080
	s_addc_u32 s13, s13, 0
	s_add_u32 s28, s34, 0x100
	s_addc_u32 s30, s35, 0
	s_mov_b32 s36, -2
	s_add_u32 s34, s12, 0xfffc0080
	s_addc_u32 s35, s13, -1
	s_add_i32 s46, 0, 0x10000
	s_cmp_eq_u32 s36, 12
	s_cselect_b32 s45, s19, s35
	s_cselect_b32 s44, s20, s34
	v_add_u32_e32 v0, s46, v175
	s_cselect_b32 s35, s15, s30
	s_cselect_b32 s34, s21, s28
	s_add_i32 s48, 0, 0x14000
	ds_read_b128 v[148:151], v0
	ds_read_b128 v[152:155], v0 offset:1024
	ds_read_b128 v[156:159], v0 offset:2048
	ds_read_b128 v[166:169], v0 offset:3072
	v_add_u32_e32 v0, s48, v175
	ds_read_b128 v[170:173], v0
	ds_read_b128 v[180:183], v0 offset:1024
	ds_read_b128 v[184:187], v0 offset:2048
	ds_read_b128 v[188:191], v0 offset:3072
	v_lshl_add_u64 v[234:235], s[12:13], 0, v[138:139]
	s_add_i32 m0, s7, 0xc000
	ds_read_b128 v[202:205], v178
	ds_read_b128 v[206:209], v178 offset:1024
	ds_read_b128 v[210:213], v178 offset:2048
	ds_read_b128 v[214:217], v178 offset:3072
	ds_read_b128 v[218:221], v178 offset:4096
	ds_read_b128 v[222:225], v178 offset:5120
	ds_read_b128 v[226:229], v178 offset:6144
	ds_read_b128 v[230:233], v178 offset:7168
	global_load_lds_dwordx4 v[234:235], off
	v_lshl_add_u64 v[234:235], s[12:13], 0, v[140:141]
	s_add_i32 m0, s7, 0xe000
	s_nop 0
	global_load_lds_dwordx4 v[234:235], off
	s_waitcnt vmcnt(8)
	s_waitcnt lgkmcnt(0)
	s_barrier
	s_setprio 1
	s_waitcnt lgkmcnt(0)
	v_mfma_f32_16x16x32_bf16 v[126:129], v[148:151], v[202:205], 0
	v_mfma_f32_16x16x32_bf16 v[122:125], v[156:159], v[202:205], 0
	v_mfma_f32_16x16x32_bf16 v[118:121], v[148:151], v[210:213], 0
	v_mfma_f32_16x16x32_bf16 v[110:113], v[156:159], v[210:213], 0
	v_mfma_f32_16x16x32_bf16 v[102:105], v[148:151], v[218:221], 0
	v_mfma_f32_16x16x32_bf16 v[94:97], v[156:159], v[218:221], 0
	v_mfma_f32_16x16x32_bf16 v[86:89], v[148:151], v[226:229], 0
	v_mfma_f32_16x16x32_bf16 v[78:81], v[156:159], v[226:229], 0
	v_mfma_f32_16x16x32_bf16 v[126:129], v[152:155], v[206:209], v[126:129]
	v_mfma_f32_16x16x32_bf16 v[122:125], v[166:169], v[206:209], v[122:125]
	v_mfma_f32_16x16x32_bf16 v[118:121], v[152:155], v[214:217], v[118:121]
	v_mfma_f32_16x16x32_bf16 v[110:113], v[166:169], v[214:217], v[110:113]
	v_mfma_f32_16x16x32_bf16 v[102:105], v[152:155], v[222:225], v[102:105]
	v_mfma_f32_16x16x32_bf16 v[94:97], v[166:169], v[222:225], v[94:97]
	v_mfma_f32_16x16x32_bf16 v[86:89], v[152:155], v[230:233], v[86:89]
	v_mfma_f32_16x16x32_bf16 v[78:81], v[166:169], v[230:233], v[78:81]
	s_setprio 0
	s_setprio 1
	v_mfma_f32_16x16x32_bf16 v[114:117], v[170:173], v[202:205], 0
	v_mfma_f32_16x16x32_bf16 v[106:109], v[184:187], v[202:205], 0
	v_mfma_f32_16x16x32_bf16 v[98:101], v[170:173], v[210:213], 0
	v_mfma_f32_16x16x32_bf16 v[90:93], v[184:187], v[210:213], 0
	v_mfma_f32_16x16x32_bf16 v[82:85], v[170:173], v[218:221], 0
	v_mfma_f32_16x16x32_bf16 v[74:77], v[184:187], v[218:221], 0
	v_mfma_f32_16x16x32_bf16 v[70:73], v[170:173], v[226:229], 0
	v_mfma_f32_16x16x32_bf16 v[66:69], v[184:187], v[226:229], 0
	v_mfma_f32_16x16x32_bf16 v[114:117], v[180:183], v[206:209], v[114:117]
	v_mfma_f32_16x16x32_bf16 v[106:109], v[188:191], v[206:209], v[106:109]
	v_mfma_f32_16x16x32_bf16 v[98:101], v[180:183], v[214:217], v[98:101]
	v_mfma_f32_16x16x32_bf16 v[90:93], v[188:191], v[214:217], v[90:93]
	v_mfma_f32_16x16x32_bf16 v[82:85], v[180:183], v[222:225], v[82:85]
	v_mfma_f32_16x16x32_bf16 v[74:77], v[188:191], v[222:225], v[74:77]
	v_mfma_f32_16x16x32_bf16 v[70:73], v[180:183], v[230:233], v[70:73]
	v_mfma_f32_16x16x32_bf16 v[66:69], v[188:191], v[230:233], v[66:69]
	s_setprio 0
	s_barrier
	s_add_i32 s46, s46, s33
	v_lshl_add_u64 v[234:235], s[34:35], 0, v[132:133]
	s_mov_b32 m0, s46
	ds_read_b128 v[202:205], v178 offset:16384
	ds_read_b128 v[206:209], v178 offset:17408
	ds_read_b128 v[210:213], v178 offset:18432
	ds_read_b128 v[214:217], v178 offset:19456
	ds_read_b128 v[218:221], v178 offset:20480
	ds_read_b128 v[222:225], v178 offset:21504
	ds_read_b128 v[226:229], v178 offset:22528
	ds_read_b128 v[230:233], v178 offset:23552
	global_load_lds_dwordx4 v[234:235], off
	s_add_i32 m0, s46, 0x2000
	s_add_u32 s46, s34, 0x40000
	v_lshl_add_u64 v[236:237], s[34:35], 0, v[136:137]
	s_addc_u32 s47, s35, 0
	s_add_i32 s48, s48, s33
	global_load_lds_dwordx4 v[236:237], off
	v_lshl_add_u64 v[238:239], s[46:47], 0, v[132:133]
	s_mov_b32 m0, s48
	v_lshl_add_u64 v[240:241], s[44:45], 0, v[134:135]
	global_load_lds_dwordx4 v[238:239], off
	v_lshl_add_u64 v[238:239], s[46:47], 0, v[136:137]
	s_add_i32 m0, s48, 0x2000
	s_nop 0
	global_load_lds_dwordx4 v[238:239], off
	v_lshl_add_u64 v[238:239], s[44:45], 0, v[130:131]
	s_mov_b32 m0, s7
	s_nop 0
	global_load_lds_dwordx4 v[238:239], off
	s_mov_b32 m0, s39
	s_nop 0
	global_load_lds_dwordx4 v[240:241], off
	s_waitcnt vmcnt(8)
	s_waitcnt lgkmcnt(0)
	s_barrier
; #define PG8_STAGE(bufoff, gbase, voff) do { _Pragma("unroll") for (int _i = 0; _i < 2; ++_i) \
;         __builtin_amdgcn_global_load_lds((const unsigned*)((const char*)(gbase) + (voff)[_i]), (LAS unsigned*)(lds + (bufoff) + ldsw + _i * 8192), 16, 0, 0); } while (0)
; #define PG8_LDA(dst, b, h) do { _Pragma("unroll") for (int m = 0; m < 4; ++m) _Pragma("unroll") for (int k = 0; k < 2; ++k) dst[m][k] = *(const LAS bf16x8*)(lds + PG8_SA(b, h) + aoff + m * 2048 + k * 1024); } while (0)
; #define PG8_LDB(dst, b, h) do { _Pragma("unroll") for (int n = 0; n < 2; ++n) _Pragma("unroll") for (int k = 0; k < 2; ++k) dst[n][k] = *(const LAS bf16x8*)(lds + PG8_SB(b, h) + boff + n * 2048 + k * 1024); } while (0)
; #define PG8_MMA(ai, bj, At, Bt) do { __builtin_amdgcn_s_setprio(1); _Pragma("unroll") for (int m = 0; m < 4; ++m) _Pragma("unroll") for (int n = 0; n < 2; ++n) _Pragma("unroll") for (int k = 0; k < 2; ++k) \
;         acc[ai][bj][m][n] = __builtin_amdgcn_mfma_f32_16x16x32_bf16(Bt[n][k], At[m][k], acc[ai][bj][m][n], 0, 0, 0); __builtin_amdgcn_s_setprio(0); } while (0)
; #define PG8_WAIT_V(n) asm volatile("s_waitcnt vmcnt(" #n ")" ::: "memory")
; #define PG8_WAIT_L(n) asm volatile("s_waitcnt lgkmcnt(" #n ")" ::: "memory")
; #define PG8_BAR __builtin_amdgcn_s_barrier()
; #define PG8_SCHED __builtin_amdgcn_sched_barrier(0)
; template <class Epi, class Sched, bool ALIGN_EPI = true>
; __device__ __forceinline__ void gemm_phase(LAS unsigned char* lds, const int wave_s, const int K, const Sched& S, const Epi& E) {
;     ...
;             PG8_WAIT_V(8); PG8_WAIT_L(0); PG8_BAR; PG8_MMA(1, 0, At, B0); PG8_MMA(1, 1, At, B1); PG8_BAR; PG8_SCHED;
;             PG8_LDB(B0, 1, 0); PG8_LDB(B1, 1, 1); PG8_SCHED; PG8_LDA(At, 1, 0); PG8_STAGE(PG8_SA(0, 1), a2 + hstep, voffA);
;             PG8_WAIT_V(8); PG8_WAIT_L(0); PG8_BAR; PG8_MMA(0, 0, At, B0); PG8_MMA(0, 1, At, B1); PG8_BAR; PG8_SCHED;
	s_setprio 1
	s_waitcnt lgkmcnt(0)
	v_mfma_f32_16x16x32_bf16 v[62:65], v[148:151], v[202:205], 0
	v_mfma_f32_16x16x32_bf16 v[58:61], v[156:159], v[202:205], 0
	v_mfma_f32_16x16x32_bf16 v[54:57], v[148:151], v[210:213], 0
	v_mfma_f32_16x16x32_bf16 v[50:53], v[156:159], v[210:213], 0
	v_mfma_f32_16x16x32_bf16 v[38:41], v[148:151], v[218:221], 0
	v_mfma_f32_16x16x32_bf16 v[34:37], v[156:159], v[218:221], 0
	v_mfma_f32_16x16x32_bf16 v[22:25], v[148:151], v[226:229], 0
	v_mfma_f32_16x16x32_bf16 v[18:21], v[156:159], v[226:229], 0
	v_mfma_f32_16x16x32_bf16 v[62:65], v[152:155], v[206:209], v[62:65]
	v_mfma_f32_16x16x32_bf16 v[58:61], v[166:169], v[206:209], v[58:61]
	v_mfma_f32_16x16x32_bf16 v[54:57], v[152:155], v[214:217], v[54:57]
	v_mfma_f32_16x16x32_bf16 v[50:53], v[166:169], v[214:217], v[50:53]
	v_mfma_f32_16x16x32_bf16 v[38:41], v[152:155], v[222:225], v[38:41]
	v_mfma_f32_16x16x32_bf16 v[34:37], v[166:169], v[222:225], v[34:37]
	v_mfma_f32_16x16x32_bf16 v[22:25], v[152:155], v[230:233], v[22:25]
	v_mfma_f32_16x16x32_bf16 v[18:21], v[166:169], v[230:233], v[18:21]
	s_setprio 0
	s_setprio 1
	v_mfma_f32_16x16x32_bf16 v[46:49], v[170:173], v[202:205], 0
	v_mfma_f32_16x16x32_bf16 v[42:45], v[184:187], v[202:205], 0
	v_mfma_f32_16x16x32_bf16 v[30:33], v[170:173], v[210:213], 0
	v_mfma_f32_16x16x32_bf16 v[26:29], v[184:187], v[210:213], 0
	v_mfma_f32_16x16x32_bf16 v[14:17], v[170:173], v[218:221], 0
	v_mfma_f32_16x16x32_bf16 v[10:13], v[184:187], v[218:221], 0
	v_mfma_f32_16x16x32_bf16 v[6:9], v[170:173], v[226:229], 0
	v_mfma_f32_16x16x32_bf16 v[2:5], v[184:187], v[226:229], 0
	v_mfma_f32_16x16x32_bf16 v[46:49], v[180:183], v[206:209], v[46:49]
	v_mfma_f32_16x16x32_bf16 v[42:45], v[188:191], v[206:209], v[42:45]
	v_mfma_f32_16x16x32_bf16 v[30:33], v[180:183], v[214:217], v[30:33]
	v_mfma_f32_16x16x32_bf16 v[26:29], v[188:191], v[214:217], v[26:29]
	v_mfma_f32_16x16x32_bf16 v[14:17], v[180:183], v[222:225], v[14:17]
	v_mfma_f32_16x16x32_bf16 v[10:13], v[188:191], v[222:225], v[10:13]
	v_mfma_f32_16x16x32_bf16 v[6:9], v[180:183], v[230:233], v[6:9]
	v_mfma_f32_16x16x32_bf16 v[2:5], v[188:191], v[230:233], v[2:5]
	s_setprio 0
	s_barrier
	s_add_i32 s46, 0, 0x18000
	v_add_u32_e32 v0, s46, v175
	s_add_i32 s47, 0, 0x1c000
	ds_read_b128 v[148:151], v0
	ds_read_b128 v[152:155], v0 offset:1024
	ds_read_b128 v[156:159], v0 offset:2048
	ds_read_b128 v[166:169], v0 offset:3072
	v_add_u32_e32 v0, s47, v175
	ds_read_b128 v[170:173], v0
	ds_read_b128 v[180:183], v0 offset:1024
	ds_read_b128 v[184:187], v0 offset:2048
	ds_read_b128 v[188:191], v0 offset:3072
	s_add_u32 s44, s44, 0x40000
	s_addc_u32 s45, s45, 0
	s_mov_b32 m0, s65
	v_lshl_add_u64 v[242:243], s[44:45], 0, v[130:131]
	ds_read_b128 v[202:205], v178 offset:32768
	ds_read_b128 v[206:209], v178 offset:33792
	ds_read_b128 v[210:213], v178 offset:34816
	ds_read_b128 v[214:217], v178 offset:35840
	ds_read_b128 v[218:221], v178 offset:36864
	ds_read_b128 v[222:225], v178 offset:37888
	ds_read_b128 v[226:229], v178 offset:38912
	ds_read_b128 v[230:233], v178 offset:39936
	global_load_lds_dwordx4 v[242:243], off
	v_lshl_add_u64 v[242:243], s[44:45], 0, v[134:135]
	s_mov_b32 m0, s68
	s_nop 0
	global_load_lds_dwordx4 v[242:243], off
	s_waitcnt vmcnt(8)
	s_waitcnt lgkmcnt(0)
	s_barrier
	s_setprio 1
	s_waitcnt lgkmcnt(0)
	v_mfma_f32_16x16x32_bf16 v[126:129], v[148:151], v[202:205], v[126:129]
	v_mfma_f32_16x16x32_bf16 v[122:125], v[156:159], v[202:205], v[122:125]
	v_mfma_f32_16x16x32_bf16 v[118:121], v[148:151], v[210:213], v[118:121]
	v_mfma_f32_16x16x32_bf16 v[110:113], v[156:159], v[210:213], v[110:113]
	v_mfma_f32_16x16x32_bf16 v[102:105], v[148:151], v[218:221], v[102:105]
	v_mfma_f32_16x16x32_bf16 v[94:97], v[156:159], v[218:221], v[94:97]
	v_mfma_f32_16x16x32_bf16 v[86:89], v[148:151], v[226:229], v[86:89]
	v_mfma_f32_16x16x32_bf16 v[78:81], v[156:159], v[226:229], v[78:81]
	v_mfma_f32_16x16x32_bf16 v[126:129], v[152:155], v[206:209], v[126:129]
	v_mfma_f32_16x16x32_bf16 v[122:125], v[166:169], v[206:209], v[122:125]
	v_mfma_f32_16x16x32_bf16 v[118:121], v[152:155], v[214:217], v[118:121]
	v_mfma_f32_16x16x32_bf16 v[110:113], v[166:169], v[214:217], v[110:113]
	v_mfma_f32_16x16x32_bf16 v[102:105], v[152:155], v[222:225], v[102:105]
	v_mfma_f32_16x16x32_bf16 v[94:97], v[166:169], v[222:225], v[94:97]
	v_mfma_f32_16x16x32_bf16 v[86:89], v[152:155], v[230:233], v[86:89]
	v_mfma_f32_16x16x32_bf16 v[78:81], v[166:169], v[230:233], v[78:81]
	s_setprio 0
	s_setprio 1
	v_mfma_f32_16x16x32_bf16 v[114:117], v[170:173], v[202:205], v[114:117]
	v_mfma_f32_16x16x32_bf16 v[106:109], v[184:187], v[202:205], v[106:109]
	v_mfma_f32_16x16x32_bf16 v[98:101], v[170:173], v[210:213], v[98:101]
	v_mfma_f32_16x16x32_bf16 v[90:93], v[184:187], v[210:213], v[90:93]
	v_mfma_f32_16x16x32_bf16 v[82:85], v[170:173], v[218:221], v[82:85]
	v_mfma_f32_16x16x32_bf16 v[74:77], v[184:187], v[218:221], v[74:77]
	v_mfma_f32_16x16x32_bf16 v[70:73], v[170:173], v[226:229], v[70:73]
	v_mfma_f32_16x16x32_bf16 v[66:69], v[184:187], v[226:229], v[66:69]
	v_mfma_f32_16x16x32_bf16 v[114:117], v[180:183], v[206:209], v[114:117]
	v_mfma_f32_16x16x32_bf16 v[106:109], v[188:191], v[206:209], v[106:109]
	v_mfma_f32_16x16x32_bf16 v[98:101], v[180:183], v[214:217], v[98:101]
	v_mfma_f32_16x16x32_bf16 v[90:93], v[188:191], v[214:217], v[90:93]
	v_mfma_f32_16x16x32_bf16 v[82:85], v[180:183], v[222:225], v[82:85]
	v_mfma_f32_16x16x32_bf16 v[74:77], v[188:191], v[222:225], v[74:77]
	v_mfma_f32_16x16x32_bf16 v[70:73], v[180:183], v[230:233], v[70:73]
	v_mfma_f32_16x16x32_bf16 v[66:69], v[188:191], v[230:233], v[66:69]
	s_setprio 0
	s_barrier
; #define PG8_STAGE(bufoff, gbase, voff) do { _Pragma("unroll") for (int _i = 0; _i < 2; ++_i) \
;         __builtin_amdgcn_global_load_lds((const unsigned*)((const char*)(gbase) + (voff)[_i]), (LAS unsigned*)(lds + (bufoff) + ldsw + _i * 8192), 16, 0, 0); } while (0)
; #define PG8_LDA(dst, b, h) do { _Pragma("unroll") for (int m = 0; m < 4; ++m) _Pragma("unroll") for (int k = 0; k < 2; ++k) dst[m][k] = *(const LAS bf16x8*)(lds + PG8_SA(b, h) + aoff + m * 2048 + k * 1024); } while (0)
; #define PG8_MMA(ai, bj, At, Bt) do { __builtin_amdgcn_s_setprio(1); _Pragma("unroll") for (int m = 0; m < 4; ++m) _Pragma("unroll") for (int n = 0; n < 2; ++n) _Pragma("unroll") for (int k = 0; k < 2; ++k) \
;         acc[ai][bj][m][n] = __builtin_amdgcn_mfma_f32_16x16x32_bf16(Bt[n][k], At[m][k], acc[ai][bj][m][n], 0, 0, 0); __builtin_amdgcn_s_setprio(0); } while (0)
; #define PG8_WAIT_V(n) asm volatile("s_waitcnt vmcnt(" #n ")" ::: "memory")
; #define PG8_WAIT_L(n) asm volatile("s_waitcnt lgkmcnt(" #n ")" ::: "memory")
; #define PG8_BAR __builtin_amdgcn_s_barrier()
; #define PG8_SCHED __builtin_amdgcn_sched_barrier(0)
; template <class Epi, class Sched, bool ALIGN_EPI = true>
; __device__ __forceinline__ void gemm_phase(LAS unsigned char* lds, const int wave_s, const int K, const Sched& S, const Epi& E) {
;     ...
;             PG8_LDA(At, 1, 1); PG8_STAGE(PG8_SB(1, 0), b3, voffB); PG8_STAGE(PG8_SB(1, 1), b3 + hstep, voffB); PG8_STAGE(PG8_SA(1, 0), a3, voffA);
;             PG8_WAIT_V(8); PG8_WAIT_L(0); PG8_BAR; PG8_MMA(1, 0, At, B0); PG8_MMA(1, 1, At, B1); PG8_BAR; PG8_SCHED;
	s_add_i32 s44, s46, s33
	v_lshl_add_u64 v[234:235], v[234:235], 0, s[22:23]
	s_mov_b32 m0, s44
	ds_read_b128 v[202:205], v178 offset:49152
	ds_read_b128 v[206:209], v178 offset:50176
	ds_read_b128 v[210:213], v178 offset:51200
	ds_read_b128 v[214:217], v178 offset:52224
	ds_read_b128 v[218:221], v178 offset:53248
	ds_read_b128 v[222:225], v178 offset:54272
	ds_read_b128 v[226:229], v178 offset:55296
	ds_read_b128 v[230:233], v178 offset:56320
	global_load_lds_dwordx4 v[234:235], off
	s_add_i32 m0, s44, 0x2000
	s_add_u32 s34, s34, 0x40080
	v_lshl_add_u64 v[234:235], v[236:237], 0, s[22:23]
	s_addc_u32 s35, s35, 0
	s_add_i32 s44, s47, s33
	global_load_lds_dwordx4 v[234:235], off
	v_lshl_add_u64 v[234:235], s[34:35], 0, v[132:133]
	s_mov_b32 m0, s44
	s_nop 0
	global_load_lds_dwordx4 v[234:235], off
	v_lshl_add_u64 v[234:235], s[34:35], 0, v[136:137]
	s_add_i32 m0, s44, 0x2000
	s_nop 0
	global_load_lds_dwordx4 v[234:235], off
	v_lshl_add_u64 v[234:235], v[238:239], 0, s[22:23]
	s_mov_b32 m0, s69
	s_nop 0
	global_load_lds_dwordx4 v[234:235], off
	v_lshl_add_u64 v[234:235], v[240:241], 0, s[22:23]
	s_mov_b32 m0, s78
	s_nop 0
	global_load_lds_dwordx4 v[234:235], off
	s_waitcnt vmcnt(8)
	s_waitcnt lgkmcnt(0)
	s_barrier
	s_setprio 1
	s_waitcnt lgkmcnt(0)
	v_mfma_f32_16x16x32_bf16 v[62:65], v[148:151], v[202:205], v[62:65]
	v_mfma_f32_16x16x32_bf16 v[58:61], v[156:159], v[202:205], v[58:61]
	v_mfma_f32_16x16x32_bf16 v[54:57], v[148:151], v[210:213], v[54:57]
	v_mfma_f32_16x16x32_bf16 v[50:53], v[156:159], v[210:213], v[50:53]
	v_mfma_f32_16x16x32_bf16 v[38:41], v[148:151], v[218:221], v[38:41]
	v_mfma_f32_16x16x32_bf16 v[34:37], v[156:159], v[218:221], v[34:37]
	v_mfma_f32_16x16x32_bf16 v[22:25], v[148:151], v[226:229], v[22:25]
	v_mfma_f32_16x16x32_bf16 v[18:21], v[156:159], v[226:229], v[18:21]
	v_mfma_f32_16x16x32_bf16 v[62:65], v[152:155], v[206:209], v[62:65]
	v_mfma_f32_16x16x32_bf16 v[58:61], v[166:169], v[206:209], v[58:61]
	v_mfma_f32_16x16x32_bf16 v[54:57], v[152:155], v[214:217], v[54:57]
	v_mfma_f32_16x16x32_bf16 v[50:53], v[166:169], v[214:217], v[50:53]
	v_mfma_f32_16x16x32_bf16 v[38:41], v[152:155], v[222:225], v[38:41]
	v_mfma_f32_16x16x32_bf16 v[34:37], v[166:169], v[222:225], v[34:37]
	v_mfma_f32_16x16x32_bf16 v[22:25], v[152:155], v[230:233], v[22:25]
	v_mfma_f32_16x16x32_bf16 v[18:21], v[166:169], v[230:233], v[18:21]
	s_setprio 0
	s_setprio 1
	v_mfma_f32_16x16x32_bf16 v[46:49], v[170:173], v[202:205], v[46:49]
	v_mfma_f32_16x16x32_bf16 v[42:45], v[184:187], v[202:205], v[42:45]
	v_mfma_f32_16x16x32_bf16 v[30:33], v[170:173], v[210:213], v[30:33]
	v_mfma_f32_16x16x32_bf16 v[26:29], v[184:187], v[210:213], v[26:29]
	v_mfma_f32_16x16x32_bf16 v[14:17], v[170:173], v[218:221], v[14:17]
	v_mfma_f32_16x16x32_bf16 v[10:13], v[184:187], v[218:221], v[10:13]
	v_mfma_f32_16x16x32_bf16 v[6:9], v[170:173], v[226:229], v[6:9]
	v_mfma_f32_16x16x32_bf16 v[2:5], v[184:187], v[226:229], v[2:5]
	v_mfma_f32_16x16x32_bf16 v[46:49], v[180:183], v[206:209], v[46:49]
	v_mfma_f32_16x16x32_bf16 v[42:45], v[188:191], v[206:209], v[42:45]
	v_mfma_f32_16x16x32_bf16 v[30:33], v[180:183], v[214:217], v[30:33]
	v_mfma_f32_16x16x32_bf16 v[26:29], v[188:191], v[214:217], v[26:29]
	v_mfma_f32_16x16x32_bf16 v[14:17], v[180:183], v[222:225], v[14:17]
	v_mfma_f32_16x16x32_bf16 v[10:13], v[188:191], v[222:225], v[10:13]
	v_mfma_f32_16x16x32_bf16 v[6:9], v[180:183], v[230:233], v[6:9]
	v_mfma_f32_16x16x32_bf16 v[2:5], v[188:191], v[230:233], v[2:5]
	s_setprio 0
	s_barrier
	s_add_i32 s36, s36, 2
	s_add_u32 s12, s12, 0x100
	s_addc_u32 s13, s13, 0
	s_add_u32 s28, s28, 0x100
	s_addc_u32 s30, s30, 0
	s_cmp_gt_u32 s36, 13
